# write-through (sc0 sc1) f32 residual stores in out-proj/FFN-out epilogues to shrink the barrier L2 writeback
# baseline (speedup 1.0000x reference)
.LBB0_1406:
	s_cmp_lt_u32 s26, 10
	s_cselect_b32 s0, s41, s43
	v_mov_b32_e32 v79, s0
	s_movk_i32 s0, 0x180
	s_cselect_b32 s0, s0, 0x500
	v_mad_i64_i32 v[80:81], s[30:31], s0, v64, 0
	s_cselect_b32 s29, s40, s42
	s_cselect_b32 s30, 0, 0xfffffe80
	v_mov_b32_e32 v78, s29
	s_cselect_b32 s29, 0, -1
	s_add_u32 s30, s10, s30
	v_lshl_add_u64 v[78:79], v[80:81], 1, v[78:79]
	s_addc_u32 s31, s11, s29
	v_lshl_add_u64 v[78:79], s[30:31], 1, v[78:79]
	s_lshl_b32 s29, s28, 14
	s_waitcnt vmcnt(0)
	v_lshl_add_u64 v[82:83], v[78:79], 0, v[68:69]
	s_add_i32 s29, s14, s29
	s_lshl_b32 s0, s0, 5
	s_waitcnt lgkmcnt(0)
	s_barrier
	s_lshl_b32 s98, s27, 14
	v_add_u32_e32 v65, s98, v88
	v_or_b32_e32 v124, s98, v89
	ds_read_b128 v[78:81], v65
	ds_read_b128 v[92:95], v65 offset:1024
	ds_read_b128 v[96:99], v65 offset:2048
	ds_read_b128 v[100:103], v65 offset:3072
	ds_read_b128 v[104:107], v124
	ds_read_b128 v[108:111], v124 offset:1024
	ds_read_b128 v[112:115], v124 offset:2048
	ds_read_b128 v[116:119], v124 offset:3072
	v_lshl_add_u64 v[128:129], v[82:83], 0, s[4:5]
	s_mov_b32 m0, s29
	v_lshl_add_u64 v[120:121], v[82:83], 0, s[0:1]
	global_load_lds_dwordx4 v[128:129], off
	v_lshl_add_u64 v[128:129], v[120:121], 0, s[4:5]
	s_add_i32 m0, s29, 0x400
	v_lshl_add_u64 v[122:123], v[66:67], 0, s[12:13]
	global_load_lds_dwordx4 v[128:129], off
	s_add_i32 m0, s29, 0x2000
	v_lshl_add_u64 v[128:129], v[122:123], 0, s[4:5]
	s_lshl_b32 s0, s27, 14
	global_load_lds_dwordx4 v[128:129], off
	s_add_i32 m0, s29, 0x2400
	s_add_i32 s0, s27, 1
	s_cmp_lg_u32 s27, 3
	s_mov_b64 s[30:31], 0x8080
	s_cselect_b32 s27, s0, 0
	s_add_i32 s0, s28, 1
	v_lshl_add_u64 v[128:129], v[122:123], 0, s[30:31]
	s_cmp_lg_u32 s28, 3
	global_load_lds_dwordx4 v[128:129], off
	s_cselect_b32 s0, s0, 0
	s_waitcnt lgkmcnt(0)
	s_lshl_b32 s28, s0, 14
	s_add_i32 s30, s14, s28
	v_mfma_f32_16x16x32_bf16 v[60:63], v[104:107], v[78:81], v[60:63]
	v_mfma_f32_16x16x32_bf16 v[56:59], v[108:111], v[78:81], v[56:59]
	s_mov_b32 m0, s30
	s_mov_b64 s[28:29], 0x80c0
	s_add_i32 s26, s26, 2
	v_mfma_f32_16x16x32_bf16 v[52:55], v[112:115], v[78:81], v[52:55]
	v_mfma_f32_16x16x32_bf16 v[48:51], v[116:119], v[78:81], v[48:51]
	v_lshl_add_u64 v[78:79], v[82:83], 0, s[6:7]
	global_load_lds_dwordx4 v[78:79], off
	v_lshl_add_u64 v[78:79], v[120:121], 0, s[6:7]
	s_add_i32 m0, s30, 0x400
	v_mfma_f32_16x16x32_bf16 v[44:47], v[104:107], v[92:95], v[44:47]
	global_load_lds_dwordx4 v[78:79], off
	s_add_i32 m0, s30, 0x2000
	v_lshl_add_u64 v[78:79], v[122:123], 0, s[6:7]
	global_load_lds_dwordx4 v[78:79], off
	v_lshl_add_u64 v[78:79], v[122:123], 0, s[28:29]
	s_add_i32 m0, s30, 0x2400
	s_lshl_b32 s28, s27, 14
	global_load_lds_dwordx4 v[78:79], off
	v_add_u32_e32 v65, s28, v88
	v_or_b32_e32 v82, s28, v89
	s_add_i32 s28, s27, 1
	v_mfma_f32_16x16x32_bf16 v[40:43], v[108:111], v[92:95], v[40:43]
	s_cmp_lg_u32 s27, 3
	s_cselect_b32 s27, s28, 0
	s_add_i32 s28, s0, 1
	v_mfma_f32_16x16x32_bf16 v[36:39], v[112:115], v[92:95], v[36:39]
	s_cmp_lg_u32 s0, 3
	s_cselect_b32 s28, s28, 0
	s_add_u32 s12, s12, 0x80
	v_mfma_f32_16x16x32_bf16 v[32:35], v[116:119], v[92:95], v[32:35]
	s_addc_u32 s13, s13, 0
	s_add_u32 s10, s10, 64
	s_addc_u32 s11, s11, 0
	v_mfma_f32_16x16x32_bf16 v[28:31], v[104:107], v[96:99], v[28:31]
	s_cmpk_eq_i32 s12, 0x780
	v_mfma_f32_16x16x32_bf16 v[24:27], v[108:111], v[96:99], v[24:27]
	v_mfma_f32_16x16x32_bf16 v[20:23], v[112:115], v[96:99], v[20:23]
	v_mfma_f32_16x16x32_bf16 v[16:19], v[116:119], v[96:99], v[16:19]
	v_mfma_f32_16x16x32_bf16 v[12:15], v[104:107], v[100:103], v[12:15]
	v_mfma_f32_16x16x32_bf16 v[8:11], v[108:111], v[100:103], v[8:11]
	v_mfma_f32_16x16x32_bf16 v[4:7], v[112:115], v[100:103], v[4:7]
	v_mfma_f32_16x16x32_bf16 v[0:3], v[116:119], v[100:103], v[0:3]
	ds_read_b128 v[78:81], v65
	ds_read_b128 v[92:95], v65 offset:1024
	ds_read_b128 v[96:99], v65 offset:2048
	ds_read_b128 v[100:103], v65 offset:3072
	ds_read_b128 v[104:107], v82
	ds_read_b128 v[108:111], v82 offset:1024
	ds_read_b128 v[112:115], v82 offset:2048
	ds_read_b128 v[116:119], v82 offset:3072
	s_waitcnt lgkmcnt(0)
	s_nop 0
	v_mfma_f32_16x16x32_bf16 v[60:63], v[104:107], v[78:81], v[60:63]
	v_mfma_f32_16x16x32_bf16 v[56:59], v[108:111], v[78:81], v[56:59]
	v_mfma_f32_16x16x32_bf16 v[52:55], v[112:115], v[78:81], v[52:55]
	v_mfma_f32_16x16x32_bf16 v[48:51], v[116:119], v[78:81], v[48:51]
	v_mfma_f32_16x16x32_bf16 v[44:47], v[104:107], v[92:95], v[44:47]
	v_mfma_f32_16x16x32_bf16 v[40:43], v[108:111], v[92:95], v[40:43]
	v_mfma_f32_16x16x32_bf16 v[36:39], v[112:115], v[92:95], v[36:39]
	v_mfma_f32_16x16x32_bf16 v[32:35], v[116:119], v[92:95], v[32:35]
	v_mfma_f32_16x16x32_bf16 v[28:31], v[104:107], v[96:99], v[28:31]
	v_mfma_f32_16x16x32_bf16 v[24:27], v[108:111], v[96:99], v[24:27]
	v_mfma_f32_16x16x32_bf16 v[20:23], v[112:115], v[96:99], v[20:23]
	v_mfma_f32_16x16x32_bf16 v[16:19], v[116:119], v[96:99], v[16:19]
	v_mfma_f32_16x16x32_bf16 v[12:15], v[104:107], v[100:103], v[12:15]
	v_mfma_f32_16x16x32_bf16 v[8:11], v[108:111], v[100:103], v[8:11]
	v_mfma_f32_16x16x32_bf16 v[4:7], v[112:115], v[100:103], v[4:7]
	v_mfma_f32_16x16x32_bf16 v[0:3], v[116:119], v[100:103], v[0:3]
	s_cbranch_scc0 .LBB0_1406
	s_waitcnt vmcnt(4)
	s_waitcnt lgkmcnt(0)
	s_barrier
	ds_read_b128 v[64:67], v88 offset:32768
	ds_read_b128 v[78:81], v88 offset:33792
	ds_read_b128 v[92:95], v88 offset:34816
	ds_read_b128 v[96:99], v88 offset:35840
	ds_read_b128 v[100:103], v89 offset:32768
	ds_read_b128 v[104:107], v89 offset:33792
	ds_read_b128 v[108:111], v89 offset:34816
	ds_read_b128 v[112:115], v89 offset:35840
	s_waitcnt lgkmcnt(0)
	s_waitcnt vmcnt(0)
	s_waitcnt lgkmcnt(0)
	s_barrier
	v_mfma_f32_16x16x32_bf16 v[56:59], v[104:107], v[64:67], v[56:59]
	s_movk_i32 s0, 0xfff
	v_readlane_b32 s36, v241, 1
	v_mfma_f32_16x16x32_bf16 v[40:43], v[104:107], v[78:81], v[40:43]
	v_readlane_b32 s44, v241, 9
	v_readlane_b32 s45, v241, 10
	s_add_i32 s2, s2, s3
	v_mfma_f32_16x16x32_bf16 v[24:27], v[104:107], v[92:95], v[24:27]
	s_add_i32 s15, s15, s16
	s_cmpk_gt_i32 s2, 0x9f
	v_readlane_b32 s37, v241, 2
	v_mfma_f32_16x16x32_bf16 v[52:55], v[108:111], v[64:67], v[52:55]
	v_readlane_b32 s38, v241, 3
	v_readlane_b32 s39, v241, 4
	v_readlane_b32 s40, v241, 5
	v_mfma_f32_16x16x32_bf16 v[36:39], v[108:111], v[78:81], v[36:39]
	v_readlane_b32 s41, v241, 6
	v_readlane_b32 s42, v241, 7
	v_readlane_b32 s43, v241, 8
	v_mfma_f32_16x16x32_bf16 v[20:23], v[108:111], v[92:95], v[20:23]
	v_readlane_b32 s46, v241, 11
	v_readlane_b32 s47, v241, 12
	v_readlane_b32 s48, v241, 13
	v_mfma_f32_16x16x32_bf16 v[60:63], v[100:103], v[64:67], v[60:63]
	v_readlane_b32 s49, v241, 14
	v_readlane_b32 s50, v241, 15
	v_readlane_b32 s51, v241, 16
	v_mfma_f32_16x16x32_bf16 v[48:51], v[112:115], v[64:67], v[48:51]
	v_mfma_f32_16x16x32_bf16 v[44:47], v[100:103], v[78:81], v[44:47]
	v_mfma_f32_16x16x32_bf16 v[32:35], v[112:115], v[78:81], v[32:35]
	v_mfma_f32_16x16x32_bf16 v[28:31], v[100:103], v[92:95], v[28:31]
	v_mfma_f32_16x16x32_bf16 v[16:19], v[112:115], v[92:95], v[16:19]
	v_mfma_f32_16x16x32_bf16 v[12:15], v[100:103], v[96:99], v[12:15]
	v_mfma_f32_16x16x32_bf16 v[8:11], v[104:107], v[96:99], v[8:11]
	v_mfma_f32_16x16x32_bf16 v[4:7], v[108:111], v[96:99], v[4:7]
	v_mfma_f32_16x16x32_bf16 v[0:3], v[112:115], v[96:99], v[0:3]
	ds_read_b128 v[64:67], v88 offset:49152
	ds_read_b128 v[78:81], v88 offset:50176
	ds_read_b128 v[92:95], v88 offset:51200
	ds_read_b128 v[96:99], v88 offset:52224
	ds_read_b128 v[100:103], v89 offset:49152
	ds_read_b128 v[104:107], v89 offset:50176
	ds_read_b128 v[108:111], v89 offset:51200
	ds_read_b128 v[112:115], v89 offset:52224
	s_waitcnt lgkmcnt(0)
	s_waitcnt lgkmcnt(0)
	s_barrier
	v_mfma_f32_16x16x32_bf16 v[120:123], v[104:107], v[64:67], v[56:59]
	v_mfma_f32_16x16x32_bf16 v[56:59], v[104:107], v[78:81], v[40:43]
	v_mfma_f32_16x16x32_bf16 v[40:43], v[104:107], v[92:95], v[24:27]
	s_nop 2
	v_add_u32_e32 v24, s24, v86
	v_mfma_f32_16x16x32_bf16 v[124:127], v[108:111], v[64:67], v[52:55]
	v_cmp_lt_i32_e32 vcc, s0, v24
	s_movk_i32 s0, 0x6000
	v_mfma_f32_16x16x32_bf16 v[52:55], v[108:111], v[78:81], v[36:39]
	v_mfma_f32_16x16x32_bf16 v[36:39], v[108:111], v[92:95], v[20:23]
	s_nop 2
	v_add_u32_e32 v21, 0xfffff000, v24
	v_lshrrev_b32_e32 v21, 12, v21
	v_add_u32_e32 v21, 1, v21
	v_or_b32_e32 v20, s25, v87
	v_cndmask_b32_e32 v21, 0, v21, vcc
	v_mad_u64_u32 v[22:23], s[10:11], v21, s0, v[74:75]
	v_ashrrev_i32_e32 v21, 31, v20
	v_mfma_f32_16x16x32_bf16 v[116:119], v[100:103], v[64:67], v[60:63]
	s_mov_b64 s[10:11], 0x2000
	s_movk_i32 s0, 0x2000
	v_mfma_f32_16x16x32_bf16 v[64:67], v[112:115], v[64:67], v[48:51]
	v_mfma_f32_16x16x32_bf16 v[60:63], v[100:103], v[78:81], v[44:47]
	v_mfma_f32_16x16x32_bf16 v[48:51], v[112:115], v[78:81], v[32:35]
	v_lshlrev_b64 v[78:79], 2, v[20:21]
	v_lshl_add_u64 v[20:21], v[22:23], 0, v[78:79]
	v_lshl_add_u64 v[20:21], v[20:21], 0, v[76:77]
	v_lshl_add_u64 v[22:23], v[20:21], 0, s[10:11]
	v_add_co_u32_e32 v20, vcc, s0, v20
	v_mfma_f32_16x16x32_bf16 v[44:47], v[100:103], v[92:95], v[28:31]
	s_nop 0
	v_addc_co_u32_e32 v21, vcc, 0, v21, vcc
	v_mfma_f32_16x16x32_bf16 v[16:19], v[112:115], v[92:95], v[16:19]
	v_or_b32_e32 v92, v24, v84
	v_or_b32_e32 v82, 32, v92
	v_or_b32_e32 v80, 48, v92
	v_mfma_f32_16x16x32_bf16 v[12:15], v[100:103], v[96:99], v[12:15]
	global_load_dwordx4 v[32:35], v[20:21], off
	global_load_dwordx4 v[28:31], v[22:23], off offset:64
	global_load_dwordx4 v[24:27], v[22:23], off offset:128
	s_nop 0
	global_load_dwordx4 v[20:23], v[22:23], off offset:192
	v_mfma_f32_16x16x32_bf16 v[8:11], v[104:107], v[96:99], v[8:11]
	v_mfma_f32_16x16x32_bf16 v[4:7], v[108:111], v[96:99], v[4:7]
	v_mfma_f32_16x16x32_bf16 v[0:3], v[112:115], v[96:99], v[0:3]
	v_or_b32_e32 v96, 16, v92
	s_nop 0
	v_mov_b32_e32 v194, v92
	v_ashrrev_i32_e32 v195, 31, v92
	v_lshlrev_b64 v[194:195], 12, v[194:195]
	v_lshl_add_u64 v[194:195], s[44:45], 0, v[194:195]
	v_lshl_add_u64 v[194:195], v[194:195], 0, v[78:79]
	v_lshl_add_u64 v[194:195], v[194:195], 0, v[76:77]
	v_mov_b32_e32 v196, v96
	v_ashrrev_i32_e32 v197, 31, v96
	v_lshlrev_b64 v[196:197], 12, v[196:197]
	v_lshl_add_u64 v[196:197], s[44:45], 0, v[196:197]
	v_lshl_add_u64 v[196:197], v[196:197], 0, v[78:79]
	v_lshl_add_u64 v[196:197], v[196:197], 0, v[76:77]
	v_mov_b32_e32 v198, v82
	v_ashrrev_i32_e32 v199, 31, v82
	v_lshlrev_b64 v[198:199], 12, v[198:199]
	v_lshl_add_u64 v[198:199], s[44:45], 0, v[198:199]
	v_lshl_add_u64 v[198:199], v[198:199], 0, v[78:79]
	v_lshl_add_u64 v[198:199], v[198:199], 0, v[76:77]
	v_mov_b32_e32 v200, v80
	v_ashrrev_i32_e32 v201, 31, v80
	v_lshlrev_b64 v[200:201], 12, v[200:201]
	v_lshl_add_u64 v[200:201], s[44:45], 0, v[200:201]
	v_lshl_add_u64 v[200:201], v[200:201], 0, v[78:79]
	v_lshl_add_u64 v[200:201], v[200:201], 0, v[76:77]
	global_load_dwordx4 v[130:133], v[194:195], off
	global_load_dwordx4 v[134:137], v[194:195], off offset:64
	global_load_dwordx4 v[138:141], v[194:195], off offset:128
	global_load_dwordx4 v[142:145], v[194:195], off offset:192
	global_load_dwordx4 v[146:149], v[196:197], off
	global_load_dwordx4 v[150:153], v[196:197], off offset:64
	global_load_dwordx4 v[154:157], v[196:197], off offset:128
	global_load_dwordx4 v[158:161], v[196:197], off offset:192
	global_load_dwordx4 v[162:165], v[198:199], off
	global_load_dwordx4 v[166:169], v[198:199], off offset:64
	global_load_dwordx4 v[170:173], v[198:199], off offset:128
	global_load_dwordx4 v[174:177], v[198:199], off offset:192
	global_load_dwordx4 v[178:181], v[200:201], off
	global_load_dwordx4 v[182:185], v[200:201], off offset:64
	global_load_dwordx4 v[186:189], v[200:201], off offset:128
	global_load_dwordx4 v[190:193], v[200:201], off offset:192
	s_waitcnt vmcnt(15)
	v_pk_mul_f32 v[130:131], v[130:131], s[8:9] op_sel_hi:[1,0]
	v_pk_mul_f32 v[132:133], v[132:133], s[8:9] op_sel_hi:[1,0]
	v_pk_fma_f32 v[130:131], v[116:117], v[32:33], v[130:131]
	v_pk_fma_f32 v[132:133], v[118:119], v[34:35], v[132:133]
	global_store_dwordx4 v[194:195], v[130:133], off sc0 sc1
	s_waitcnt vmcnt(15)
	v_pk_mul_f32 v[134:135], v[134:135], s[8:9] op_sel_hi:[1,0]
	v_pk_mul_f32 v[136:137], v[136:137], s[8:9] op_sel_hi:[1,0]
	v_pk_fma_f32 v[134:135], v[120:121], v[28:29], v[134:135]
	v_pk_fma_f32 v[136:137], v[122:123], v[30:31], v[136:137]
	global_store_dwordx4 v[194:195], v[134:137], off offset:64 sc0 sc1
	s_waitcnt vmcnt(15)
	v_pk_mul_f32 v[138:139], v[138:139], s[8:9] op_sel_hi:[1,0]
	v_pk_mul_f32 v[140:141], v[140:141], s[8:9] op_sel_hi:[1,0]
	v_pk_fma_f32 v[138:139], v[124:125], v[24:25], v[138:139]
	v_pk_fma_f32 v[140:141], v[126:127], v[26:27], v[140:141]
	global_store_dwordx4 v[194:195], v[138:141], off offset:128 sc0 sc1
	s_waitcnt vmcnt(15)
	v_pk_mul_f32 v[142:143], v[142:143], s[8:9] op_sel_hi:[1,0]
	v_pk_fma_f32 v[64:65], v[64:65], v[20:21], v[142:143]
	v_pk_mul_f32 v[142:143], v[144:145], s[8:9] op_sel_hi:[1,0]
	v_pk_fma_f32 v[66:67], v[66:67], v[22:23], v[142:143]
	global_store_dwordx4 v[194:195], v[64:67], off offset:192 sc0 sc1
	s_waitcnt vmcnt(15)
	v_pk_mul_f32 v[146:147], v[146:147], s[8:9] op_sel_hi:[1,0]
	v_pk_fma_f32 v[60:61], v[60:61], v[32:33], v[146:147]
	v_pk_mul_f32 v[146:147], v[148:149], s[8:9] op_sel_hi:[1,0]
	v_pk_fma_f32 v[62:63], v[62:63], v[34:35], v[146:147]
	global_store_dwordx4 v[196:197], v[60:63], off sc0 sc1
	s_waitcnt vmcnt(15)
	v_pk_mul_f32 v[150:151], v[150:151], s[8:9] op_sel_hi:[1,0]
	v_pk_fma_f32 v[56:57], v[56:57], v[28:29], v[150:151]
	v_pk_mul_f32 v[150:151], v[152:153], s[8:9] op_sel_hi:[1,0]
	v_pk_fma_f32 v[58:59], v[58:59], v[30:31], v[150:151]
	global_store_dwordx4 v[196:197], v[56:59], off offset:64 sc0 sc1
	s_waitcnt vmcnt(15)
	v_pk_mul_f32 v[154:155], v[154:155], s[8:9] op_sel_hi:[1,0]
	v_pk_fma_f32 v[52:53], v[52:53], v[24:25], v[154:155]
	v_pk_mul_f32 v[154:155], v[156:157], s[8:9] op_sel_hi:[1,0]
	v_pk_fma_f32 v[54:55], v[54:55], v[26:27], v[154:155]
	global_store_dwordx4 v[196:197], v[52:55], off offset:128 sc0 sc1
	s_waitcnt vmcnt(15)
	v_pk_mul_f32 v[158:159], v[158:159], s[8:9] op_sel_hi:[1,0]
	v_pk_fma_f32 v[48:49], v[48:49], v[20:21], v[158:159]
	v_pk_mul_f32 v[158:159], v[160:161], s[8:9] op_sel_hi:[1,0]
	v_pk_fma_f32 v[50:51], v[50:51], v[22:23], v[158:159]
	global_store_dwordx4 v[196:197], v[48:51], off offset:192 sc0 sc1
	s_waitcnt vmcnt(15)
	v_pk_mul_f32 v[162:163], v[162:163], s[8:9] op_sel_hi:[1,0]
	v_pk_fma_f32 v[44:45], v[44:45], v[32:33], v[162:163]
	v_pk_mul_f32 v[162:163], v[164:165], s[8:9] op_sel_hi:[1,0]
	v_pk_fma_f32 v[46:47], v[46:47], v[34:35], v[162:163]
	global_store_dwordx4 v[198:199], v[44:47], off sc0 sc1
	s_waitcnt vmcnt(15)
	v_pk_mul_f32 v[166:167], v[166:167], s[8:9] op_sel_hi:[1,0]
	v_pk_fma_f32 v[40:41], v[40:41], v[28:29], v[166:167]
	v_pk_mul_f32 v[166:167], v[168:169], s[8:9] op_sel_hi:[1,0]
	v_pk_fma_f32 v[42:43], v[42:43], v[30:31], v[166:167]
	global_store_dwordx4 v[198:199], v[40:43], off offset:64 sc0 sc1
	s_waitcnt vmcnt(15)
	v_pk_mul_f32 v[170:171], v[170:171], s[8:9] op_sel_hi:[1,0]
	v_pk_fma_f32 v[36:37], v[36:37], v[24:25], v[170:171]
	v_pk_mul_f32 v[170:171], v[172:173], s[8:9] op_sel_hi:[1,0]
	v_pk_fma_f32 v[38:39], v[38:39], v[26:27], v[170:171]
	global_store_dwordx4 v[198:199], v[36:39], off offset:128 sc0 sc1
	s_waitcnt vmcnt(15)
	v_pk_mul_f32 v[174:175], v[174:175], s[8:9] op_sel_hi:[1,0]
	v_pk_fma_f32 v[16:17], v[16:17], v[20:21], v[174:175]
	v_pk_mul_f32 v[174:175], v[176:177], s[8:9] op_sel_hi:[1,0]
	v_pk_fma_f32 v[18:19], v[18:19], v[22:23], v[174:175]
	global_store_dwordx4 v[198:199], v[16:19], off offset:192 sc0 sc1
	s_waitcnt vmcnt(15)
	v_pk_mul_f32 v[178:179], v[178:179], s[8:9] op_sel_hi:[1,0]
	v_pk_fma_f32 v[12:13], v[12:13], v[32:33], v[178:179]
	v_pk_mul_f32 v[178:179], v[180:181], s[8:9] op_sel_hi:[1,0]
	v_pk_fma_f32 v[14:15], v[14:15], v[34:35], v[178:179]
	global_store_dwordx4 v[200:201], v[12:15], off sc0 sc1
	s_waitcnt vmcnt(15)
	v_pk_mul_f32 v[182:183], v[182:183], s[8:9] op_sel_hi:[1,0]
	v_pk_fma_f32 v[8:9], v[8:9], v[28:29], v[182:183]
	v_pk_mul_f32 v[182:183], v[184:185], s[8:9] op_sel_hi:[1,0]
	v_pk_fma_f32 v[10:11], v[10:11], v[30:31], v[182:183]
	global_store_dwordx4 v[200:201], v[8:11], off offset:64 sc0 sc1
	s_waitcnt vmcnt(15)
	v_pk_mul_f32 v[186:187], v[186:187], s[8:9] op_sel_hi:[1,0]
	v_pk_fma_f32 v[4:5], v[4:5], v[24:25], v[186:187]
	v_pk_mul_f32 v[186:187], v[188:189], s[8:9] op_sel_hi:[1,0]
	v_pk_fma_f32 v[6:7], v[6:7], v[26:27], v[186:187]
	global_store_dwordx4 v[200:201], v[4:7], off offset:128 sc0 sc1
	s_waitcnt vmcnt(15)
	v_pk_mul_f32 v[190:191], v[190:191], s[8:9] op_sel_hi:[1,0]
	v_pk_fma_f32 v[0:1], v[0:1], v[20:21], v[190:191]
	v_pk_mul_f32 v[190:191], v[192:193], s[8:9] op_sel_hi:[1,0]
	v_pk_fma_f32 v[2:3], v[2:3], v[22:23], v[190:191]
	global_store_dwordx4 v[200:201], v[0:3], off offset:192 sc0 sc1
	s_cbranch_scc0 .LBB0_1405

.LBB0_1577:
	s_lshl_b32 s36, s35, 14
	s_waitcnt vmcnt(0)
	v_lshl_add_u64 v[80:81], v[66:67], 0, s[16:17]
	s_add_i32 s36, s19, s36
	s_waitcnt lgkmcnt(0)
	s_barrier
	s_lshl_b32 s98, s34, 14
	v_add_u32_e32 v120, s98, v86
	v_or_b32_e32 v121, s98, v87
	ds_read_b128 v[76:79], v120
	ds_read_b128 v[90:93], v120 offset:1024
	ds_read_b128 v[94:97], v120 offset:2048
	ds_read_b128 v[98:101], v120 offset:3072
	ds_read_b128 v[102:105], v121
	ds_read_b128 v[106:109], v121 offset:1024
	ds_read_b128 v[110:113], v121 offset:2048
	ds_read_b128 v[114:117], v121 offset:3072
	v_lshl_add_u64 v[126:127], v[80:81], 0, s[6:7]
	s_mov_b32 m0, s36
	v_lshl_add_u64 v[118:119], v[64:65], 0, s[16:17]
	global_load_lds_dwordx4 v[126:127], off
	v_lshl_add_u64 v[126:127], v[80:81], 0, s[8:9]
	s_add_i32 m0, s36, 0x400
	s_nop 0
	global_load_lds_dwordx4 v[126:127], off
	s_add_i32 m0, s36, 0x2000
	v_lshl_add_u64 v[126:127], v[118:119], 0, s[6:7]
	global_load_lds_dwordx4 v[126:127], off
	s_add_i32 m0, s36, 0x2400
	s_lshl_b32 s36, s34, 14
	s_add_i32 s36, s34, 1
	s_cmp_lg_u32 s34, 3
	s_cselect_b32 s34, s36, 0
	s_add_i32 s36, s35, 1
	v_lshl_add_u64 v[126:127], v[118:119], 0, s[8:9]
	s_cmp_lg_u32 s35, 3
	global_load_lds_dwordx4 v[126:127], off
	s_cselect_b32 s35, s36, 0
	s_waitcnt lgkmcnt(0)
	s_lshl_b32 s36, s35, 14
	s_add_i32 s36, s19, s36
	v_mfma_f32_16x16x32_bf16 v[60:63], v[102:105], v[76:79], v[60:63]
	v_mfma_f32_16x16x32_bf16 v[56:59], v[106:109], v[76:79], v[56:59]
	s_mov_b32 m0, s36
	v_mfma_f32_16x16x32_bf16 v[52:55], v[110:113], v[76:79], v[52:55]
	v_mfma_f32_16x16x32_bf16 v[48:51], v[114:117], v[76:79], v[48:51]
	v_lshl_add_u64 v[76:77], v[80:81], 0, s[10:11]
	global_load_lds_dwordx4 v[76:77], off
	v_lshl_add_u64 v[76:77], v[80:81], 0, s[12:13]
	s_add_i32 m0, s36, 0x400
	v_mfma_f32_16x16x32_bf16 v[44:47], v[102:105], v[90:93], v[44:47]
	global_load_lds_dwordx4 v[76:77], off
	s_add_i32 m0, s36, 0x2000
	v_lshl_add_u64 v[76:77], v[118:119], 0, s[10:11]
	global_load_lds_dwordx4 v[76:77], off
	v_lshl_add_u64 v[76:77], v[118:119], 0, s[12:13]
	s_add_i32 m0, s36, 0x2400
	v_mfma_f32_16x16x32_bf16 v[40:43], v[106:109], v[90:93], v[40:43]
	global_load_lds_dwordx4 v[76:77], off
	s_lshl_b32 s36, s34, 14
	v_mfma_f32_16x16x32_bf16 v[36:39], v[110:113], v[90:93], v[36:39]
	v_add_u32_e32 v80, s36, v86
	v_or_b32_e32 v81, s36, v87
	s_add_i32 s36, s34, 1
	v_mfma_f32_16x16x32_bf16 v[32:35], v[114:117], v[90:93], v[32:35]
	s_cmp_lg_u32 s34, 3
	s_cselect_b32 s34, s36, 0
	s_add_i32 s36, s35, 1
	v_mfma_f32_16x16x32_bf16 v[28:31], v[102:105], v[94:97], v[28:31]
	s_cmp_lg_u32 s35, 3
	s_cselect_b32 s35, s36, 0
	s_add_u32 s16, s16, 0x80
	v_mfma_f32_16x16x32_bf16 v[24:27], v[106:109], v[94:97], v[24:27]
	s_addc_u32 s17, s17, 0
	s_cmpk_eq_i32 s16, 0x1580
	v_mfma_f32_16x16x32_bf16 v[20:23], v[110:113], v[94:97], v[20:23]
	v_mfma_f32_16x16x32_bf16 v[16:19], v[114:117], v[94:97], v[16:19]
	v_mfma_f32_16x16x32_bf16 v[12:15], v[102:105], v[98:101], v[12:15]
	v_mfma_f32_16x16x32_bf16 v[8:11], v[106:109], v[98:101], v[8:11]
	v_mfma_f32_16x16x32_bf16 v[4:7], v[110:113], v[98:101], v[4:7]
	v_mfma_f32_16x16x32_bf16 v[0:3], v[114:117], v[98:101], v[0:3]
	ds_read_b128 v[76:79], v80
	ds_read_b128 v[90:93], v80 offset:1024
	ds_read_b128 v[94:97], v80 offset:2048
	ds_read_b128 v[98:101], v80 offset:3072
	ds_read_b128 v[102:105], v81
	ds_read_b128 v[106:109], v81 offset:1024
	ds_read_b128 v[110:113], v81 offset:2048
	ds_read_b128 v[114:117], v81 offset:3072
	s_waitcnt lgkmcnt(0)
	s_nop 0
	v_mfma_f32_16x16x32_bf16 v[60:63], v[102:105], v[76:79], v[60:63]
	v_mfma_f32_16x16x32_bf16 v[56:59], v[106:109], v[76:79], v[56:59]
	v_mfma_f32_16x16x32_bf16 v[52:55], v[110:113], v[76:79], v[52:55]
	v_mfma_f32_16x16x32_bf16 v[48:51], v[114:117], v[76:79], v[48:51]
	v_mfma_f32_16x16x32_bf16 v[44:47], v[102:105], v[90:93], v[44:47]
	v_mfma_f32_16x16x32_bf16 v[40:43], v[106:109], v[90:93], v[40:43]
	v_mfma_f32_16x16x32_bf16 v[36:39], v[110:113], v[90:93], v[36:39]
	v_mfma_f32_16x16x32_bf16 v[32:35], v[114:117], v[90:93], v[32:35]
	v_mfma_f32_16x16x32_bf16 v[28:31], v[102:105], v[94:97], v[28:31]
	v_mfma_f32_16x16x32_bf16 v[24:27], v[106:109], v[94:97], v[24:27]
	v_mfma_f32_16x16x32_bf16 v[20:23], v[110:113], v[94:97], v[20:23]
	v_mfma_f32_16x16x32_bf16 v[16:19], v[114:117], v[94:97], v[16:19]
	v_mfma_f32_16x16x32_bf16 v[12:15], v[102:105], v[98:101], v[12:15]
	v_mfma_f32_16x16x32_bf16 v[8:11], v[106:109], v[98:101], v[8:11]
	v_mfma_f32_16x16x32_bf16 v[4:7], v[110:113], v[98:101], v[4:7]
	v_mfma_f32_16x16x32_bf16 v[0:3], v[114:117], v[98:101], v[0:3]
	s_cbranch_scc0 .LBB0_1577
	s_waitcnt vmcnt(4)
	s_waitcnt lgkmcnt(0)
	s_barrier
	ds_read_b128 v[64:67], v86 offset:32768
	ds_read_b128 v[76:79], v86 offset:33792
	ds_read_b128 v[90:93], v86 offset:34816
	ds_read_b128 v[94:97], v86 offset:35840
	ds_read_b128 v[98:101], v87 offset:32768
	ds_read_b128 v[102:105], v87 offset:33792
	ds_read_b128 v[106:109], v87 offset:34816
	ds_read_b128 v[110:113], v87 offset:35840
	s_waitcnt lgkmcnt(0)
	s_waitcnt vmcnt(0)
	s_waitcnt lgkmcnt(0)
	s_barrier
	v_mfma_f32_16x16x32_bf16 v[56:59], v[102:105], v[64:67], v[56:59]
	s_movk_i32 s16, 0xfff
	v_readlane_b32 s36, v241, 1
	v_mfma_f32_16x16x32_bf16 v[40:43], v[102:105], v[76:79], v[40:43]
	v_readlane_b32 s44, v241, 9
	v_readlane_b32 s45, v241, 10
	s_add_i32 s2, s2, s3
	v_mfma_f32_16x16x32_bf16 v[24:27], v[102:105], v[90:93], v[24:27]
	s_add_i32 s20, s20, s21
	v_readlane_b32 s37, v241, 2
	v_readlane_b32 s38, v241, 3
	v_mfma_f32_16x16x32_bf16 v[52:55], v[106:109], v[64:67], v[52:55]
	v_readlane_b32 s39, v241, 4
	v_readlane_b32 s40, v241, 5
	v_readlane_b32 s41, v241, 6
	v_mfma_f32_16x16x32_bf16 v[36:39], v[106:109], v[76:79], v[36:39]
	v_readlane_b32 s42, v241, 7
	v_readlane_b32 s43, v241, 8
	v_readlane_b32 s46, v241, 11
	v_mfma_f32_16x16x32_bf16 v[20:23], v[106:109], v[90:93], v[20:23]
	v_readlane_b32 s47, v241, 12
	v_readlane_b32 s48, v241, 13
	v_readlane_b32 s49, v241, 14
	v_mfma_f32_16x16x32_bf16 v[60:63], v[98:101], v[64:67], v[60:63]
	v_readlane_b32 s50, v241, 15
	v_readlane_b32 s51, v241, 16
	v_mfma_f32_16x16x32_bf16 v[48:51], v[110:113], v[64:67], v[48:51]
	v_mfma_f32_16x16x32_bf16 v[44:47], v[98:101], v[76:79], v[44:47]
	v_mfma_f32_16x16x32_bf16 v[32:35], v[110:113], v[76:79], v[32:35]
	v_mfma_f32_16x16x32_bf16 v[28:31], v[98:101], v[90:93], v[28:31]
	v_mfma_f32_16x16x32_bf16 v[16:19], v[110:113], v[90:93], v[16:19]
	v_mfma_f32_16x16x32_bf16 v[12:15], v[98:101], v[94:97], v[12:15]
	v_mfma_f32_16x16x32_bf16 v[8:11], v[102:105], v[94:97], v[8:11]
	v_mfma_f32_16x16x32_bf16 v[4:7], v[106:109], v[94:97], v[4:7]
	v_mfma_f32_16x16x32_bf16 v[0:3], v[110:113], v[94:97], v[0:3]
	ds_read_b128 v[64:67], v86 offset:49152
	ds_read_b128 v[76:79], v86 offset:50176
	ds_read_b128 v[90:93], v86 offset:51200
	ds_read_b128 v[94:97], v86 offset:52224
	ds_read_b128 v[98:101], v87 offset:49152
	ds_read_b128 v[102:105], v87 offset:50176
	ds_read_b128 v[106:109], v87 offset:51200
	ds_read_b128 v[110:113], v87 offset:52224
	s_waitcnt lgkmcnt(0)
	s_waitcnt lgkmcnt(0)
	s_barrier
	v_mfma_f32_16x16x32_bf16 v[118:121], v[102:105], v[64:67], v[56:59]
	v_mfma_f32_16x16x32_bf16 v[56:59], v[102:105], v[76:79], v[40:43]
	v_mfma_f32_16x16x32_bf16 v[40:43], v[102:105], v[90:93], v[24:27]
	s_nop 2
	v_add_u32_e32 v24, s31, v84
	v_mfma_f32_16x16x32_bf16 v[122:125], v[106:109], v[64:67], v[52:55]
	v_cmp_lt_i32_e32 vcc, s16, v24
	s_movk_i32 s16, 0x6000
	v_mfma_f32_16x16x32_bf16 v[52:55], v[106:109], v[76:79], v[36:39]
	v_mfma_f32_16x16x32_bf16 v[36:39], v[106:109], v[90:93], v[20:23]
	s_nop 2
	v_add_u32_e32 v21, 0xfffff000, v24
	v_lshrrev_b32_e32 v21, 12, v21
	v_add_u32_e32 v21, 1, v21
	v_or_b32_e32 v20, s33, v85
	v_cndmask_b32_e32 v21, 0, v21, vcc
	v_mad_u64_u32 v[22:23], s[16:17], v21, s16, v[74:75]
	v_ashrrev_i32_e32 v21, 31, v20
	v_mfma_f32_16x16x32_bf16 v[114:117], v[98:101], v[64:67], v[60:63]
	s_mov_b64 s[16:17], 0x5000
	v_mfma_f32_16x16x32_bf16 v[64:67], v[110:113], v[64:67], v[48:51]
	v_mfma_f32_16x16x32_bf16 v[60:63], v[98:101], v[76:79], v[44:47]
	v_mfma_f32_16x16x32_bf16 v[48:51], v[110:113], v[76:79], v[32:35]
	v_lshlrev_b64 v[76:77], 2, v[20:21]
	v_lshl_add_u64 v[20:21], v[22:23], 0, v[76:77]
	v_lshl_add_u64 v[20:21], v[20:21], 0, v[68:69]
	v_lshl_add_u64 v[22:23], v[20:21], 0, s[16:17]
	s_movk_i32 s16, 0x5000
	v_add_co_u32_e32 v20, vcc, s16, v20
	v_mfma_f32_16x16x32_bf16 v[44:47], v[98:101], v[90:93], v[28:31]
	s_nop 0
	v_addc_co_u32_e32 v21, vcc, 0, v21, vcc
	v_mfma_f32_16x16x32_bf16 v[16:19], v[110:113], v[90:93], v[16:19]
	v_or_b32_e32 v90, v24, v82
	v_or_b32_e32 v80, 32, v90
	v_or_b32_e32 v78, 48, v90
	v_mfma_f32_16x16x32_bf16 v[12:15], v[98:101], v[94:97], v[12:15]
	global_load_dwordx4 v[32:35], v[20:21], off
	global_load_dwordx4 v[28:31], v[22:23], off offset:64
	global_load_dwordx4 v[24:27], v[22:23], off offset:128
	s_nop 0
	global_load_dwordx4 v[20:23], v[22:23], off offset:192
	v_mfma_f32_16x16x32_bf16 v[8:11], v[102:105], v[94:97], v[8:11]
	v_mfma_f32_16x16x32_bf16 v[4:7], v[106:109], v[94:97], v[4:7]
	v_mfma_f32_16x16x32_bf16 v[0:3], v[110:113], v[94:97], v[0:3]
	v_or_b32_e32 v94, 16, v90
	s_nop 0
	v_mov_b32_e32 v192, v90
	v_ashrrev_i32_e32 v193, 31, v90
	v_lshlrev_b64 v[192:193], 12, v[192:193]
	v_lshl_add_u64 v[192:193], s[44:45], 0, v[192:193]
	v_lshl_add_u64 v[192:193], v[192:193], 0, v[76:77]
	v_lshl_add_u64 v[192:193], v[192:193], 0, v[68:69]
	v_mov_b32_e32 v194, v94
	v_ashrrev_i32_e32 v195, 31, v94
	v_lshlrev_b64 v[194:195], 12, v[194:195]
	v_lshl_add_u64 v[194:195], s[44:45], 0, v[194:195]
	v_lshl_add_u64 v[194:195], v[194:195], 0, v[76:77]
	v_lshl_add_u64 v[194:195], v[194:195], 0, v[68:69]
	v_mov_b32_e32 v196, v80
	v_ashrrev_i32_e32 v197, 31, v80
	v_lshlrev_b64 v[196:197], 12, v[196:197]
	v_lshl_add_u64 v[196:197], s[44:45], 0, v[196:197]
	v_lshl_add_u64 v[196:197], v[196:197], 0, v[76:77]
	v_lshl_add_u64 v[196:197], v[196:197], 0, v[68:69]
	v_mov_b32_e32 v198, v78
	v_ashrrev_i32_e32 v199, 31, v78
	v_lshlrev_b64 v[198:199], 12, v[198:199]
	v_lshl_add_u64 v[198:199], s[44:45], 0, v[198:199]
	v_lshl_add_u64 v[198:199], v[198:199], 0, v[76:77]
	v_lshl_add_u64 v[198:199], v[198:199], 0, v[68:69]
	global_load_dwordx4 v[128:131], v[192:193], off
	global_load_dwordx4 v[132:135], v[192:193], off offset:64
	global_load_dwordx4 v[136:139], v[192:193], off offset:128
	global_load_dwordx4 v[140:143], v[192:193], off offset:192
	global_load_dwordx4 v[144:147], v[194:195], off
	global_load_dwordx4 v[148:151], v[194:195], off offset:64
	global_load_dwordx4 v[152:155], v[194:195], off offset:128
	global_load_dwordx4 v[156:159], v[194:195], off offset:192
	global_load_dwordx4 v[160:163], v[196:197], off
	global_load_dwordx4 v[164:167], v[196:197], off offset:64
	global_load_dwordx4 v[168:171], v[196:197], off offset:128
	global_load_dwordx4 v[172:175], v[196:197], off offset:192
	global_load_dwordx4 v[176:179], v[198:199], off
	global_load_dwordx4 v[180:183], v[198:199], off offset:64
	global_load_dwordx4 v[184:187], v[198:199], off offset:128
	global_load_dwordx4 v[188:191], v[198:199], off offset:192
	s_waitcnt vmcnt(15)
	v_pk_mul_f32 v[128:129], v[128:129], s[14:15] op_sel_hi:[1,0]
	v_pk_mul_f32 v[130:131], v[130:131], s[14:15] op_sel_hi:[1,0]
	v_pk_fma_f32 v[128:129], v[114:115], v[32:33], v[128:129]
	v_pk_fma_f32 v[130:131], v[116:117], v[34:35], v[130:131]
	global_store_dwordx4 v[192:193], v[128:131], off sc0 sc1
	s_waitcnt vmcnt(15)
	v_pk_mul_f32 v[132:133], v[132:133], s[14:15] op_sel_hi:[1,0]
	v_pk_mul_f32 v[134:135], v[134:135], s[14:15] op_sel_hi:[1,0]
	v_pk_fma_f32 v[132:133], v[118:119], v[28:29], v[132:133]
	v_pk_fma_f32 v[134:135], v[120:121], v[30:31], v[134:135]
	global_store_dwordx4 v[192:193], v[132:135], off offset:64 sc0 sc1
	s_waitcnt vmcnt(15)
	v_pk_mul_f32 v[136:137], v[136:137], s[14:15] op_sel_hi:[1,0]
	v_pk_mul_f32 v[138:139], v[138:139], s[14:15] op_sel_hi:[1,0]
	v_pk_fma_f32 v[136:137], v[122:123], v[24:25], v[136:137]
	v_pk_fma_f32 v[138:139], v[124:125], v[26:27], v[138:139]
	global_store_dwordx4 v[192:193], v[136:139], off offset:128 sc0 sc1
	s_waitcnt vmcnt(15)
	v_pk_mul_f32 v[140:141], v[140:141], s[14:15] op_sel_hi:[1,0]
	v_pk_fma_f32 v[64:65], v[64:65], v[20:21], v[140:141]
	v_pk_mul_f32 v[140:141], v[142:143], s[14:15] op_sel_hi:[1,0]
	v_pk_fma_f32 v[66:67], v[66:67], v[22:23], v[140:141]
	global_store_dwordx4 v[192:193], v[64:67], off offset:192 sc0 sc1
	s_waitcnt vmcnt(15)
	v_pk_mul_f32 v[144:145], v[144:145], s[14:15] op_sel_hi:[1,0]
	v_pk_fma_f32 v[60:61], v[60:61], v[32:33], v[144:145]
	v_pk_mul_f32 v[144:145], v[146:147], s[14:15] op_sel_hi:[1,0]
	v_pk_fma_f32 v[62:63], v[62:63], v[34:35], v[144:145]
	global_store_dwordx4 v[194:195], v[60:63], off sc0 sc1
	s_waitcnt vmcnt(15)
	v_pk_mul_f32 v[148:149], v[148:149], s[14:15] op_sel_hi:[1,0]
	v_pk_fma_f32 v[56:57], v[56:57], v[28:29], v[148:149]
	v_pk_mul_f32 v[148:149], v[150:151], s[14:15] op_sel_hi:[1,0]
	v_pk_fma_f32 v[58:59], v[58:59], v[30:31], v[148:149]
	global_store_dwordx4 v[194:195], v[56:59], off offset:64 sc0 sc1
	s_waitcnt vmcnt(15)
	v_pk_mul_f32 v[152:153], v[152:153], s[14:15] op_sel_hi:[1,0]
	v_pk_fma_f32 v[52:53], v[52:53], v[24:25], v[152:153]
	v_pk_mul_f32 v[152:153], v[154:155], s[14:15] op_sel_hi:[1,0]
	v_pk_fma_f32 v[54:55], v[54:55], v[26:27], v[152:153]
	global_store_dwordx4 v[194:195], v[52:55], off offset:128 sc0 sc1
	s_waitcnt vmcnt(15)
	v_pk_mul_f32 v[156:157], v[156:157], s[14:15] op_sel_hi:[1,0]
	v_pk_fma_f32 v[48:49], v[48:49], v[20:21], v[156:157]
	v_pk_mul_f32 v[156:157], v[158:159], s[14:15] op_sel_hi:[1,0]
	v_pk_fma_f32 v[50:51], v[50:51], v[22:23], v[156:157]
	global_store_dwordx4 v[194:195], v[48:51], off offset:192 sc0 sc1
	s_waitcnt vmcnt(15)
	v_pk_mul_f32 v[160:161], v[160:161], s[14:15] op_sel_hi:[1,0]
	v_pk_fma_f32 v[44:45], v[44:45], v[32:33], v[160:161]
	v_pk_mul_f32 v[160:161], v[162:163], s[14:15] op_sel_hi:[1,0]
	v_pk_fma_f32 v[46:47], v[46:47], v[34:35], v[160:161]
	global_store_dwordx4 v[196:197], v[44:47], off sc0 sc1
	s_waitcnt vmcnt(15)
	v_pk_mul_f32 v[164:165], v[164:165], s[14:15] op_sel_hi:[1,0]
	v_pk_fma_f32 v[40:41], v[40:41], v[28:29], v[164:165]
	v_pk_mul_f32 v[164:165], v[166:167], s[14:15] op_sel_hi:[1,0]
	v_pk_fma_f32 v[42:43], v[42:43], v[30:31], v[164:165]
	global_store_dwordx4 v[196:197], v[40:43], off offset:64 sc0 sc1
	s_waitcnt vmcnt(15)
	v_pk_mul_f32 v[168:169], v[168:169], s[14:15] op_sel_hi:[1,0]
	v_pk_fma_f32 v[36:37], v[36:37], v[24:25], v[168:169]
	v_pk_mul_f32 v[168:169], v[170:171], s[14:15] op_sel_hi:[1,0]
	v_pk_fma_f32 v[38:39], v[38:39], v[26:27], v[168:169]
	global_store_dwordx4 v[196:197], v[36:39], off offset:128 sc0 sc1
	s_waitcnt vmcnt(15)
	v_pk_mul_f32 v[172:173], v[172:173], s[14:15] op_sel_hi:[1,0]
	v_pk_fma_f32 v[16:17], v[16:17], v[20:21], v[172:173]
	v_pk_mul_f32 v[172:173], v[174:175], s[14:15] op_sel_hi:[1,0]
	v_pk_fma_f32 v[18:19], v[18:19], v[22:23], v[172:173]
	global_store_dwordx4 v[196:197], v[16:19], off offset:192 sc0 sc1
	s_waitcnt vmcnt(15)
	v_pk_mul_f32 v[176:177], v[176:177], s[14:15] op_sel_hi:[1,0]
	v_pk_fma_f32 v[12:13], v[12:13], v[32:33], v[176:177]
	v_pk_mul_f32 v[176:177], v[178:179], s[14:15] op_sel_hi:[1,0]
	v_pk_fma_f32 v[14:15], v[14:15], v[34:35], v[176:177]
	global_store_dwordx4 v[198:199], v[12:15], off sc0 sc1
	s_waitcnt vmcnt(15)
	v_pk_mul_f32 v[180:181], v[180:181], s[14:15] op_sel_hi:[1,0]
	v_pk_fma_f32 v[8:9], v[8:9], v[28:29], v[180:181]
	v_pk_mul_f32 v[180:181], v[182:183], s[14:15] op_sel_hi:[1,0]
	v_pk_fma_f32 v[10:11], v[10:11], v[30:31], v[180:181]
	global_store_dwordx4 v[198:199], v[8:11], off offset:64 sc0 sc1
	s_waitcnt vmcnt(15)
	v_pk_mul_f32 v[184:185], v[184:185], s[14:15] op_sel_hi:[1,0]
	v_pk_fma_f32 v[4:5], v[4:5], v[24:25], v[184:185]
	v_pk_mul_f32 v[184:185], v[186:187], s[14:15] op_sel_hi:[1,0]
	v_pk_fma_f32 v[6:7], v[6:7], v[26:27], v[184:185]
	global_store_dwordx4 v[198:199], v[4:7], off offset:128 sc0 sc1
	s_waitcnt vmcnt(15)
	v_pk_mul_f32 v[188:189], v[188:189], s[14:15] op_sel_hi:[1,0]
	v_pk_fma_f32 v[0:1], v[0:1], v[20:21], v[188:189]
	v_pk_mul_f32 v[188:189], v[190:191], s[14:15] op_sel_hi:[1,0]
	s_add_i32 s15, s15, s30
	v_pk_fma_f32 v[2:3], v[2:3], v[22:23], v[188:189]
	s_cmpk_gt_i32 s2, 0x9f
	global_store_dwordx4 v[198:199], v[0:3], off offset:192 sc0 sc1
	s_cbranch_scc0 .LBB0_1576

.LBB0_2892:
	s_cmp_lt_u32 s46, 10
	s_cselect_b32 s52, s42, 0x500
	s_cselect_b32 s10, s57, s59
	s_cselect_b32 s49, s56, s58
	s_cselect_b32 s54, 0, 0xfffffe80
	v_mad_i64_i32 v[92:93], s[50:51], s52, v64, 0
	s_cselect_b32 s53, 0, -1
	v_mov_b32_e32 v90, s49
	v_mov_b32_e32 v91, s10
	s_add_u32 s50, s24, s54
	v_lshl_add_u64 v[90:91], v[92:93], 1, v[90:91]
	s_addc_u32 s51, s25, s53
	s_lshl_b32 s49, s47, 14
	v_lshl_add_u64 v[90:91], s[50:51], 1, v[90:91]
	s_waitcnt vmcnt(0)
	s_lshl_b32 s10, s52, 5
	s_add_i32 s49, s28, s49
	v_lshl_add_u64 v[120:121], v[90:91], 0, v[68:69]
	s_waitcnt lgkmcnt(0)
	s_barrier
	v_lshl_add_u64 v[90:91], v[120:121], 0, s[12:13]
	v_lshl_add_u64 v[122:123], v[120:121], 0, s[10:11]
	s_mov_b32 m0, s49
	v_lshl_add_u64 v[118:119], v[66:67], 0, s[26:27]
	global_load_lds_dwordx4 v[90:91], off
	v_lshl_add_u64 v[90:91], v[122:123], 0, s[12:13]
	s_add_i32 m0, s49, 0x400
	v_lshl_add_u64 v[78:79], v[118:119], 0, s[12:13]
	global_load_lds_dwordx4 v[90:91], off
	s_add_i32 m0, s49, 0x2000
	s_lshl_b32 s52, s48, 14
	global_load_lds_dwordx4 v[78:79], off
	s_add_i32 m0, s49, 0x2400
	s_add_i32 s10, s48, 1
	s_cmp_lg_u32 s48, 3
	s_cselect_b32 s10, s10, 0
	s_add_i32 s48, s47, 1
	v_lshl_add_u64 v[80:81], v[118:119], 0, s[14:15]
	s_cmp_lg_u32 s47, 3
	global_load_lds_dwordx4 v[80:81], off
	s_cselect_b32 s47, s48, 0
	v_add_u32_e32 v65, s52, v86
	v_or_b32_e32 v124, s52, v87
	ds_read_b128 v[78:81], v65
	ds_read_b128 v[90:93], v65 offset:1024
	ds_read_b128 v[94:97], v65 offset:2048
	ds_read_b128 v[98:101], v65 offset:3072
	ds_read_b128 v[102:105], v124
	ds_read_b128 v[106:109], v124 offset:1024
	ds_read_b128 v[110:113], v124 offset:2048
	ds_read_b128 v[114:117], v124 offset:3072
	s_waitcnt lgkmcnt(0)
	s_lshl_b32 s48, s47, 14
	s_add_i32 s48, s28, s48
	v_mfma_f32_16x16x32_bf16 v[44:47], v[102:105], v[90:93], v[44:47]
	v_mfma_f32_16x16x32_bf16 v[40:43], v[106:109], v[90:93], v[40:43]
	s_mov_b32 m0, s48
	s_add_i32 s46, s46, 2
	v_mfma_f32_16x16x32_bf16 v[36:39], v[110:113], v[90:93], v[36:39]
	v_mfma_f32_16x16x32_bf16 v[32:35], v[114:117], v[90:93], v[32:35]
	v_lshl_add_u64 v[90:91], v[120:121], 0, s[16:17]
	v_lshl_add_u64 v[92:93], v[122:123], 0, s[16:17]
	global_load_lds_dwordx4 v[90:91], off
	s_add_i32 m0, s48, 0x400
	v_mfma_f32_16x16x32_bf16 v[60:63], v[102:105], v[78:81], v[60:63]
	global_load_lds_dwordx4 v[92:93], off
	s_add_i32 m0, s48, 0x2000
	v_mfma_f32_16x16x32_bf16 v[56:59], v[106:109], v[78:81], v[56:59]
	v_mfma_f32_16x16x32_bf16 v[52:55], v[110:113], v[78:81], v[52:55]
	v_mfma_f32_16x16x32_bf16 v[48:51], v[114:117], v[78:81], v[48:51]
	v_lshl_add_u64 v[78:79], v[118:119], 0, s[16:17]
	v_lshl_add_u64 v[80:81], v[118:119], 0, s[18:19]
	global_load_lds_dwordx4 v[78:79], off
	s_add_i32 m0, s48, 0x2400
	s_lshl_b32 s48, s10, 14
	global_load_lds_dwordx4 v[80:81], off
	v_add_u32_e32 v65, s48, v86
	v_or_b32_e32 v118, s48, v87
	s_add_i32 s48, s10, 1
	v_mfma_f32_16x16x32_bf16 v[28:31], v[102:105], v[94:97], v[28:31]
	s_cmp_lg_u32 s10, 3
	s_cselect_b32 s48, s48, 0
	s_add_i32 s10, s47, 1
	v_mfma_f32_16x16x32_bf16 v[20:23], v[106:109], v[94:97], v[20:23]
	s_cmp_lg_u32 s47, 3
	s_cselect_b32 s47, s10, 0
	s_add_u32 s26, s26, 0x80
	v_mfma_f32_16x16x32_bf16 v[16:19], v[110:113], v[94:97], v[16:19]
	s_addc_u32 s27, s27, 0
	s_add_u32 s24, s24, 64
	s_addc_u32 s25, s25, 0
	v_mfma_f32_16x16x32_bf16 v[12:15], v[114:117], v[94:97], v[12:15]
	s_cmpk_eq_i32 s26, 0x780
	v_mfma_f32_16x16x32_bf16 v[8:11], v[102:105], v[98:101], v[8:11]
	v_mfma_f32_16x16x32_bf16 v[4:7], v[106:109], v[98:101], v[4:7]
	v_mfma_f32_16x16x32_bf16 v[0:3], v[110:113], v[98:101], v[0:3]
	v_mfma_f32_16x16x32_bf16 v[24:27], v[114:117], v[98:101], v[24:27]
	ds_read_b128 v[78:81], v65
	ds_read_b128 v[90:93], v65 offset:1024
	ds_read_b128 v[94:97], v65 offset:2048
	ds_read_b128 v[98:101], v65 offset:3072
	ds_read_b128 v[102:105], v118
	ds_read_b128 v[106:109], v118 offset:1024
	ds_read_b128 v[110:113], v118 offset:2048
	ds_read_b128 v[114:117], v118 offset:3072
	s_waitcnt lgkmcnt(0)
	s_nop 0
	v_mfma_f32_16x16x32_bf16 v[60:63], v[102:105], v[78:81], v[60:63]
	v_mfma_f32_16x16x32_bf16 v[56:59], v[106:109], v[78:81], v[56:59]
	v_mfma_f32_16x16x32_bf16 v[52:55], v[110:113], v[78:81], v[52:55]
	v_mfma_f32_16x16x32_bf16 v[48:51], v[114:117], v[78:81], v[48:51]
	v_mfma_f32_16x16x32_bf16 v[44:47], v[102:105], v[90:93], v[44:47]
	v_mfma_f32_16x16x32_bf16 v[40:43], v[106:109], v[90:93], v[40:43]
	v_mfma_f32_16x16x32_bf16 v[36:39], v[110:113], v[90:93], v[36:39]
	v_mfma_f32_16x16x32_bf16 v[32:35], v[114:117], v[90:93], v[32:35]
	v_mfma_f32_16x16x32_bf16 v[28:31], v[102:105], v[94:97], v[28:31]
	v_mfma_f32_16x16x32_bf16 v[20:23], v[106:109], v[94:97], v[20:23]
	v_mfma_f32_16x16x32_bf16 v[16:19], v[110:113], v[94:97], v[16:19]
	v_mfma_f32_16x16x32_bf16 v[12:15], v[114:117], v[94:97], v[12:15]
	v_mfma_f32_16x16x32_bf16 v[8:11], v[102:105], v[98:101], v[8:11]
	v_mfma_f32_16x16x32_bf16 v[4:7], v[106:109], v[98:101], v[4:7]
	v_mfma_f32_16x16x32_bf16 v[0:3], v[110:113], v[98:101], v[0:3]
	v_mfma_f32_16x16x32_bf16 v[24:27], v[114:117], v[98:101], v[24:27]
	s_cbranch_scc0 .LBB0_2892
	s_waitcnt vmcnt(4)
	s_waitcnt lgkmcnt(0)
	s_barrier
	ds_read_b128 v[64:67], v86 offset:32768
	ds_read_b128 v[78:81], v86 offset:33792
	ds_read_b128 v[90:93], v86 offset:34816
	ds_read_b128 v[94:97], v86 offset:35840
	ds_read_b128 v[98:101], v87 offset:32768
	ds_read_b128 v[102:105], v87 offset:33792
	ds_read_b128 v[106:109], v87 offset:34816
	ds_read_b128 v[110:113], v87 offset:35840
	s_waitcnt lgkmcnt(0)
	s_waitcnt vmcnt(0)
	s_waitcnt lgkmcnt(0)
	s_barrier
	v_mfma_f32_16x16x32_bf16 v[158:161], v[102:105], v[90:93], v[20:23]
	s_add_i32 s2, s2, s3
	s_add_i32 s31, s31, s33
	v_mfma_f32_16x16x32_bf16 v[114:117], v[98:101], v[64:67], v[60:63]
	v_add_u32_e32 v22, s44, v84
	v_or_b32_e32 v20, s45, v85
	v_cmp_lt_i32_e32 vcc, s43, v22
	v_mfma_f32_16x16x32_bf16 v[118:121], v[102:105], v[64:67], v[56:59]
	v_ashrrev_i32_e32 v21, 31, v20
	v_readlane_b32 s44, v241, 1
	v_readlane_b32 s52, v241, 9
	v_mfma_f32_16x16x32_bf16 v[122:125], v[106:109], v[64:67], v[52:55]
	v_readlane_b32 s53, v241, 10
	s_cmpk_gt_i32 s2, 0x9f
	v_readlane_b32 s45, v241, 2
	v_mfma_f32_16x16x32_bf16 v[126:129], v[110:113], v[64:67], v[48:51]
	v_readlane_b32 s46, v241, 3
	v_readlane_b32 s47, v241, 4
	v_readlane_b32 s48, v241, 5
	v_mfma_f32_16x16x32_bf16 v[64:67], v[106:109], v[90:93], v[16:19]
	v_readlane_b32 s49, v241, 6
	v_readlane_b32 s50, v241, 7
	v_readlane_b32 s51, v241, 8
	v_add_u32_e32 v16, 0xfffff000, v22
	v_lshrrev_b32_e32 v16, 12, v16
	v_add_u32_e32 v16, 6, v16
	v_mfma_f32_16x16x32_bf16 v[60:63], v[110:113], v[90:93], v[12:15]
	v_readlane_b32 s54, v241, 11
	v_readlane_b32 s55, v241, 12
	v_readlane_b32 s56, v241, 13
	v_cndmask_b32_e32 v12, 5, v16, vcc
	v_mfma_f32_16x16x32_bf16 v[130:133], v[98:101], v[78:81], v[44:47]
	v_mad_u64_u32 v[12:13], s[24:25], v12, s30, v[74:75]
	v_readlane_b32 s57, v241, 14
	v_mfma_f32_16x16x32_bf16 v[134:137], v[102:105], v[78:81], v[40:43]
	v_readlane_b32 s58, v241, 15
	v_readlane_b32 s59, v241, 16
	v_mfma_f32_16x16x32_bf16 v[138:141], v[106:109], v[78:81], v[36:39]
	v_mfma_f32_16x16x32_bf16 v[142:145], v[110:113], v[78:81], v[32:35]
	v_lshlrev_b64 v[78:79], 2, v[20:21]
	v_mfma_f32_16x16x32_bf16 v[52:55], v[98:101], v[94:97], v[8:11]
	s_nop 2
	v_lshl_add_u64 v[8:9], v[12:13], 0, v[78:79]
	v_lshl_add_u64 v[8:9], v[8:9], 0, v[76:77]
	v_mfma_f32_16x16x32_bf16 v[146:149], v[98:101], v[90:93], v[28:31]
	ds_read_b128 v[150:153], v86 offset:49152
	ds_read_b128 v[154:157], v86 offset:50176
	ds_read_b128 v[56:59], v86 offset:51200
	ds_read_b128 v[28:31], v86 offset:52224
	ds_read_b128 v[44:47], v87 offset:49152
	ds_read_b128 v[40:43], v87 offset:50176
	ds_read_b128 v[36:39], v87 offset:51200
	ds_read_b128 v[32:35], v87 offset:52224
	s_waitcnt lgkmcnt(0)
	v_add_co_u32_e32 v14, vcc, s29, v8
	s_waitcnt lgkmcnt(0)
	s_barrier
	v_lshl_add_u64 v[12:13], v[8:9], 0, s[20:21]
	v_or_b32_e32 v98, v22, v82
	v_addc_co_u32_e32 v15, vcc, 0, v9, vcc
	v_mfma_f32_16x16x32_bf16 v[20:23], v[106:109], v[94:97], v[0:3]
	v_or_b32_e32 v162, 16, v98
	v_or_b32_e32 v164, 32, v98
	v_or_b32_e32 v80, 48, v98
	global_load_dwordx4 v[0:3], v[12:13], off offset:64
	global_load_dwordx4 v[8:11], v[12:13], off offset:128
	global_load_dwordx4 v[16:19], v[14:15], off
	s_nop 0
	global_load_dwordx4 v[12:15], v[12:13], off offset:192
	v_mfma_f32_16x16x32_bf16 v[48:51], v[102:105], v[94:97], v[4:7]
	v_mov_b32_e32 v236, v98
	v_ashrrev_i32_e32 v237, 31, v98
	v_lshlrev_b64 v[236:237], 12, v[236:237]
	v_lshl_add_u64 v[236:237], s[52:53], 0, v[236:237]
	v_lshl_add_u64 v[236:237], v[236:237], 0, v[78:79]
	v_lshl_add_u64 v[236:237], v[236:237], 0, v[76:77]
	v_mov_b32_e32 v238, v162
	v_ashrrev_i32_e32 v239, 31, v162
	v_lshlrev_b64 v[238:239], 12, v[238:239]
	v_lshl_add_u64 v[238:239], s[52:53], 0, v[238:239]
	v_lshl_add_u64 v[238:239], v[238:239], 0, v[78:79]
	v_lshl_add_u64 v[238:239], v[238:239], 0, v[76:77]
	v_mov_b32_e32 v242, v164
	v_ashrrev_i32_e32 v243, 31, v164
	v_lshlrev_b64 v[242:243], 12, v[242:243]
	v_lshl_add_u64 v[242:243], s[52:53], 0, v[242:243]
	v_lshl_add_u64 v[242:243], v[242:243], 0, v[78:79]
	v_lshl_add_u64 v[242:243], v[242:243], 0, v[76:77]
	v_mov_b32_e32 v244, v80
	v_ashrrev_i32_e32 v245, 31, v80
	v_lshlrev_b64 v[244:245], 12, v[244:245]
	v_lshl_add_u64 v[244:245], s[52:53], 0, v[244:245]
	v_lshl_add_u64 v[244:245], v[244:245], 0, v[78:79]
	v_lshl_add_u64 v[244:245], v[244:245], 0, v[76:77]
	global_load_dwordx4 v[168:171], v[236:237], off
	global_load_dwordx4 v[172:175], v[236:237], off offset:64
	global_load_dwordx4 v[176:179], v[236:237], off offset:128
	global_load_dwordx4 v[180:183], v[236:237], off offset:192
	global_load_dwordx4 v[184:187], v[238:239], off
	global_load_dwordx4 v[188:191], v[238:239], off offset:64
	global_load_dwordx4 v[192:195], v[238:239], off offset:128
	global_load_dwordx4 v[196:199], v[238:239], off offset:192
	global_load_dwordx4 v[200:203], v[242:243], off
	global_load_dwordx4 v[204:207], v[242:243], off offset:64
	global_load_dwordx4 v[208:211], v[242:243], off offset:128
	global_load_dwordx4 v[212:215], v[242:243], off offset:192
	global_load_dwordx4 v[216:219], v[244:245], off
	global_load_dwordx4 v[220:223], v[244:245], off offset:64
	global_load_dwordx4 v[228:231], v[244:245], off offset:128
	global_load_dwordx4 v[232:235], v[244:245], off offset:192
	v_mfma_f32_16x16x32_bf16 v[4:7], v[110:113], v[94:97], v[24:27]
	v_mfma_f32_16x16x32_bf16 v[90:93], v[40:43], v[150:153], v[118:121]
	s_waitcnt vmcnt(15)
	v_pk_mul_f32 v[168:169], v[168:169], s[22:23] op_sel_hi:[1,0]
	v_mfma_f32_16x16x32_bf16 v[24:27], v[44:47], v[150:153], v[114:117]
	v_mul_f32_e64 v170, v170, s22
	v_mul_f32_e64 v171, v171, s22
	s_waitcnt vmcnt(14)
	v_pk_mul_f32 v[172:173], v[172:173], s[22:23] op_sel_hi:[1,0]
	v_pk_mul_f32 v[174:175], v[174:175], s[22:23] op_sel_hi:[1,0]
	v_mfma_f32_16x16x32_bf16 v[94:97], v[36:39], v[150:153], v[122:125]
	s_waitcnt vmcnt(13)
	v_mul_f32_e64 v176, v176, s22
	v_mul_f32_e64 v177, v177, s22
	v_pk_mul_f32 v[178:179], v[178:179], s[22:23] op_sel_hi:[1,0]
	v_pk_fma_f32 v[24:25], v[24:25], v[16:17], v[168:169]
	v_mfma_f32_16x16x32_bf16 v[102:105], v[32:35], v[150:153], v[126:129]
	v_fma_f32 v26, v26, v18, v170
	v_fma_f32 v27, v27, v19, v171
	v_pk_fma_f32 v[90:91], v[90:91], v[0:1], v[172:173]
	v_pk_fma_f32 v[92:93], v[92:93], v[2:3], v[174:175]
	v_pk_fma_f32 v[94:95], v[94:95], v[8:9], v[176:177]
	v_pk_fma_f32 v[96:97], v[96:97], v[10:11], v[178:179]
	v_mfma_f32_16x16x32_bf16 v[114:117], v[44:47], v[154:157], v[130:133]
	s_waitcnt vmcnt(12)
	v_pk_mul_f32 v[180:181], v[180:181], s[22:23] op_sel_hi:[1,0]
	v_pk_mul_f32 v[182:183], v[182:183], s[22:23] op_sel_hi:[1,0]
	v_pk_fma_f32 v[168:169], v[102:103], v[12:13], v[180:181]
	v_pk_fma_f32 v[170:171], v[104:105], v[14:15], v[182:183]
	global_store_dwordx4 v[236:237], v[24:27], off sc0 sc1
	global_store_dwordx4 v[236:237], v[90:93], off offset:64 sc0 sc1
	global_store_dwordx4 v[236:237], v[94:97], off offset:128 sc0 sc1
	global_store_dwordx4 v[236:237], v[168:171], off offset:192 sc0 sc1
	v_mfma_f32_16x16x32_bf16 v[122:125], v[40:43], v[154:157], v[134:137]
	v_mfma_f32_16x16x32_bf16 v[90:93], v[36:39], v[154:157], v[138:141]
	s_waitcnt vmcnt(15)
	v_pk_mul_f32 v[184:185], v[184:185], s[22:23] op_sel_hi:[1,0]
	v_mfma_f32_16x16x32_bf16 v[102:105], v[32:35], v[154:157], v[142:145]
	v_mul_f32_e64 v186, v186, s22
	v_mul_f32_e64 v187, v187, s22
	s_waitcnt vmcnt(14)
	v_pk_mul_f32 v[188:189], v[188:189], s[22:23] op_sel_hi:[1,0]
	v_pk_mul_f32 v[190:191], v[190:191], s[22:23] op_sel_hi:[1,0]
	s_waitcnt vmcnt(13)
	v_pk_mul_f32 v[192:193], v[192:193], s[22:23] op_sel_hi:[1,0]
	v_pk_mul_f32 v[194:195], v[194:195], s[22:23] op_sel_hi:[1,0]
	s_waitcnt vmcnt(12)
	v_pk_mul_f32 v[196:197], v[196:197], s[22:23] op_sel_hi:[1,0]
	v_pk_mul_f32 v[198:199], v[198:199], s[22:23] op_sel_hi:[1,0]
	v_pk_fma_f32 v[184:185], v[114:115], v[16:17], v[184:185]
	v_pk_fma_f32 v[186:187], v[116:117], v[18:19], v[186:187]
	v_pk_fma_f32 v[188:189], v[122:123], v[0:1], v[188:189]
	v_pk_fma_f32 v[190:191], v[124:125], v[2:3], v[190:191]
	v_pk_fma_f32 v[90:91], v[90:91], v[8:9], v[192:193]
	v_pk_fma_f32 v[92:93], v[92:93], v[10:11], v[194:195]
	v_pk_fma_f32 v[192:193], v[102:103], v[12:13], v[196:197]
	v_pk_fma_f32 v[194:195], v[104:105], v[14:15], v[198:199]
	global_store_dwordx4 v[238:239], v[184:187], off sc0 sc1
	global_store_dwordx4 v[238:239], v[188:191], off offset:64 sc0 sc1
	global_store_dwordx4 v[238:239], v[90:93], off offset:128 sc0 sc1
	global_store_dwordx4 v[238:239], v[192:195], off offset:192 sc0 sc1
	v_mfma_f32_16x16x32_bf16 v[176:179], v[44:47], v[56:59], v[146:149]
	v_mfma_f32_16x16x32_bf16 v[90:93], v[40:43], v[56:59], v[158:161]
	s_waitcnt vmcnt(15)
	v_pk_mul_f32 v[200:201], v[200:201], s[22:23] op_sel_hi:[1,0]
	v_mfma_f32_16x16x32_bf16 v[64:67], v[36:39], v[56:59], v[64:67]
	v_mul_f32_e64 v202, v202, s22
	v_mul_f32_e64 v203, v203, s22
	s_nop 1
	v_pk_fma_f32 v[200:201], v[176:177], v[16:17], v[200:201]
	s_nop 0
	v_pk_fma_f32 v[202:203], v[178:179], v[18:19], v[202:203]
	v_mfma_f32_16x16x32_bf16 v[56:59], v[32:35], v[56:59], v[60:63]
	s_waitcnt vmcnt(14)
	v_mul_f32_e64 v60, v204, s22
	v_mul_f32_e64 v61, v205, s22
	v_pk_mul_f32 v[62:63], v[206:207], s[22:23] op_sel_hi:[1,0]
	s_waitcnt vmcnt(13)
	v_pk_mul_f32 v[204:205], v[208:209], s[22:23] op_sel_hi:[1,0]
	v_pk_mul_f32 v[206:207], v[210:211], s[22:23] op_sel_hi:[1,0]
	s_waitcnt vmcnt(12)
	v_pk_mul_f32 v[208:209], v[212:213], s[22:23] op_sel_hi:[1,0]
	v_pk_mul_f32 v[210:211], v[214:215], s[22:23] op_sel_hi:[1,0]
	v_pk_fma_f32 v[60:61], v[90:91], v[0:1], v[60:61]
	v_pk_fma_f32 v[62:63], v[92:93], v[2:3], v[62:63]
	v_pk_fma_f32 v[64:65], v[64:65], v[8:9], v[204:205]
	v_pk_fma_f32 v[66:67], v[66:67], v[10:11], v[206:207]
	v_pk_fma_f32 v[56:57], v[56:57], v[12:13], v[208:209]
	v_pk_fma_f32 v[58:59], v[58:59], v[14:15], v[210:211]
	global_store_dwordx4 v[242:243], v[200:203], off sc0 sc1
	global_store_dwordx4 v[242:243], v[60:63], off offset:64 sc0 sc1
	global_store_dwordx4 v[242:243], v[64:67], off offset:128 sc0 sc1
	global_store_dwordx4 v[242:243], v[56:59], off offset:192 sc0 sc1
	v_mfma_f32_16x16x32_bf16 v[44:47], v[44:47], v[28:31], v[52:55]
	v_mfma_f32_16x16x32_bf16 v[40:43], v[40:43], v[28:31], v[48:51]
	s_waitcnt vmcnt(15)
	v_pk_mul_f32 v[216:217], v[216:217], s[22:23] op_sel_hi:[1,0]
	v_mfma_f32_16x16x32_bf16 v[20:23], v[36:39], v[28:31], v[20:23]
	v_mul_f32_e64 v218, v218, s22
	v_mul_f32_e64 v219, v219, s22
	s_nop 1
	v_pk_fma_f32 v[16:17], v[44:45], v[16:17], v[216:217]
	s_nop 0
	v_pk_fma_f32 v[18:19], v[46:47], v[18:19], v[218:219]
	v_mfma_f32_16x16x32_bf16 v[4:7], v[32:35], v[28:31], v[4:7]
	s_waitcnt vmcnt(14)
	v_mul_f32_e64 v28, v220, s22
	v_mul_f32_e64 v29, v221, s22
	v_pk_mul_f32 v[30:31], v[222:223], s[22:23] op_sel_hi:[1,0]
	s_waitcnt vmcnt(13)
	v_pk_mul_f32 v[32:33], v[228:229], s[22:23] op_sel_hi:[1,0]
	v_pk_mul_f32 v[34:35], v[230:231], s[22:23] op_sel_hi:[1,0]
	v_pk_fma_f32 v[0:1], v[40:41], v[0:1], v[28:29]
	v_pk_fma_f32 v[2:3], v[42:43], v[2:3], v[30:31]
	v_pk_fma_f32 v[8:9], v[20:21], v[8:9], v[32:33]
	v_pk_fma_f32 v[10:11], v[22:23], v[10:11], v[34:35]
	s_waitcnt vmcnt(12)
	v_pk_mul_f32 v[36:37], v[232:233], s[22:23] op_sel_hi:[1,0]
	v_pk_mul_f32 v[38:39], v[234:235], s[22:23] op_sel_hi:[1,0]
	v_pk_fma_f32 v[4:5], v[4:5], v[12:13], v[36:37]
	v_pk_fma_f32 v[6:7], v[6:7], v[14:15], v[38:39]
	global_store_dwordx4 v[244:245], v[16:19], off sc0 sc1
	global_store_dwordx4 v[244:245], v[0:3], off offset:64 sc0 sc1
	global_store_dwordx4 v[244:245], v[8:11], off offset:128 sc0 sc1
	global_store_dwordx4 v[244:245], v[4:7], off offset:192 sc0 sc1
	s_cbranch_scc0 .LBB0_2891

.LBB0_3063:
	s_lshl_b32 s41, s39, 14
	s_waitcnt vmcnt(0)
	v_lshl_add_u64 v[116:117], v[74:75], 0, s[18:19]
	s_add_i32 s41, s21, s41
	s_waitcnt lgkmcnt(0)
	s_barrier
	s_lshl_b32 s98, s40, 14
	v_add_u32_e32 v120, s98, v80
	v_or_b32_e32 v121, s98, v81
	ds_read_b128 v[84:87], v120
	ds_read_b128 v[88:91], v120 offset:1024
	ds_read_b128 v[92:95], v120 offset:2048
	ds_read_b128 v[96:99], v120 offset:3072
	ds_read_b128 v[100:103], v121
	ds_read_b128 v[104:107], v121 offset:1024
	ds_read_b128 v[108:111], v121 offset:2048
	ds_read_b128 v[112:115], v121 offset:3072
	v_lshl_add_u64 v[162:163], v[116:117], 0, s[6:7]
	s_mov_b32 m0, s41
	v_lshl_add_u64 v[118:119], v[72:73], 0, s[18:19]
	v_lshl_add_u64 v[164:165], v[116:117], 0, s[8:9]
	global_load_lds_dwordx4 v[162:163], off
	s_add_i32 m0, s41, 0x400
	v_lshl_add_u64 v[166:167], v[118:119], 0, s[6:7]
	global_load_lds_dwordx4 v[164:165], off
	s_add_i32 m0, s41, 0x2000
	s_lshl_b32 s42, s40, 14
	global_load_lds_dwordx4 v[166:167], off
	s_add_i32 m0, s41, 0x2400
	s_add_i32 s41, s40, 1
	s_cmp_lg_u32 s40, 3
	s_cselect_b32 s40, s41, 0
	s_add_i32 s41, s39, 1
	v_lshl_add_u64 v[168:169], v[118:119], 0, s[8:9]
	s_cmp_lg_u32 s39, 3
	global_load_lds_dwordx4 v[168:169], off
	s_cselect_b32 s39, s41, 0
	s_waitcnt lgkmcnt(0)
	s_lshl_b32 s41, s39, 14
	s_add_i32 s41, s21, s41
	v_mfma_f32_16x16x32_bf16 v[60:63], v[100:103], v[84:87], v[60:63]
	v_mfma_f32_16x16x32_bf16 v[56:59], v[104:107], v[84:87], v[56:59]
	s_mov_b32 m0, s41
	v_mfma_f32_16x16x32_bf16 v[52:55], v[108:111], v[84:87], v[52:55]
	v_mfma_f32_16x16x32_bf16 v[48:51], v[112:115], v[84:87], v[48:51]
	v_lshl_add_u64 v[84:85], v[116:117], 0, s[10:11]
	v_lshl_add_u64 v[86:87], v[116:117], 0, s[12:13]
	global_load_lds_dwordx4 v[84:85], off
	s_add_i32 m0, s41, 0x400
	v_mfma_f32_16x16x32_bf16 v[44:47], v[100:103], v[88:91], v[44:47]
	global_load_lds_dwordx4 v[86:87], off
	s_add_i32 m0, s41, 0x2000
	v_mfma_f32_16x16x32_bf16 v[40:43], v[104:107], v[88:91], v[40:43]
	v_mfma_f32_16x16x32_bf16 v[36:39], v[108:111], v[88:91], v[36:39]
	v_mfma_f32_16x16x32_bf16 v[32:35], v[112:115], v[88:91], v[32:35]
	v_lshl_add_u64 v[88:89], v[118:119], 0, s[10:11]
	v_lshl_add_u64 v[90:91], v[118:119], 0, s[12:13]
	global_load_lds_dwordx4 v[88:89], off
	s_add_i32 m0, s41, 0x2400
	v_mfma_f32_16x16x32_bf16 v[28:31], v[100:103], v[92:95], v[28:31]
	global_load_lds_dwordx4 v[90:91], off
	s_lshl_b32 s41, s40, 14
	v_mfma_f32_16x16x32_bf16 v[24:27], v[104:107], v[92:95], v[24:27]
	v_add_u32_e32 v116, s41, v80
	v_or_b32_e32 v117, s41, v81
	s_add_i32 s41, s40, 1
	v_mfma_f32_16x16x32_bf16 v[16:19], v[108:111], v[92:95], v[16:19]
	s_cmp_lg_u32 s40, 3
	s_cselect_b32 s40, s41, 0
	s_add_i32 s41, s39, 1
	v_mfma_f32_16x16x32_bf16 v[12:15], v[112:115], v[92:95], v[12:15]
	s_cmp_lg_u32 s39, 3
	s_cselect_b32 s39, s41, 0
	s_add_u32 s18, s18, 0x80
	v_mfma_f32_16x16x32_bf16 v[8:11], v[100:103], v[96:99], v[8:11]
	s_addc_u32 s19, s19, 0
	s_cmpk_eq_i32 s18, 0x1580
	v_mfma_f32_16x16x32_bf16 v[4:7], v[104:107], v[96:99], v[4:7]
	v_mfma_f32_16x16x32_bf16 v[0:3], v[108:111], v[96:99], v[0:3]
	v_mfma_f32_16x16x32_bf16 v[20:23], v[112:115], v[96:99], v[20:23]
	ds_read_b128 v[84:87], v116
	ds_read_b128 v[88:91], v116 offset:1024
	ds_read_b128 v[92:95], v116 offset:2048
	ds_read_b128 v[96:99], v116 offset:3072
	ds_read_b128 v[100:103], v117
	ds_read_b128 v[104:107], v117 offset:1024
	ds_read_b128 v[108:111], v117 offset:2048
	ds_read_b128 v[112:115], v117 offset:3072
	s_waitcnt lgkmcnt(0)
	s_nop 0
	v_mfma_f32_16x16x32_bf16 v[60:63], v[100:103], v[84:87], v[60:63]
	v_mfma_f32_16x16x32_bf16 v[56:59], v[104:107], v[84:87], v[56:59]
	v_mfma_f32_16x16x32_bf16 v[52:55], v[108:111], v[84:87], v[52:55]
	v_mfma_f32_16x16x32_bf16 v[48:51], v[112:115], v[84:87], v[48:51]
	v_mfma_f32_16x16x32_bf16 v[44:47], v[100:103], v[88:91], v[44:47]
	v_mfma_f32_16x16x32_bf16 v[40:43], v[104:107], v[88:91], v[40:43]
	v_mfma_f32_16x16x32_bf16 v[36:39], v[108:111], v[88:91], v[36:39]
	v_mfma_f32_16x16x32_bf16 v[32:35], v[112:115], v[88:91], v[32:35]
	v_mfma_f32_16x16x32_bf16 v[28:31], v[100:103], v[92:95], v[28:31]
	v_mfma_f32_16x16x32_bf16 v[24:27], v[104:107], v[92:95], v[24:27]
	v_mfma_f32_16x16x32_bf16 v[16:19], v[108:111], v[92:95], v[16:19]
	v_mfma_f32_16x16x32_bf16 v[12:15], v[112:115], v[92:95], v[12:15]
	v_mfma_f32_16x16x32_bf16 v[8:11], v[100:103], v[96:99], v[8:11]
	v_mfma_f32_16x16x32_bf16 v[4:7], v[104:107], v[96:99], v[4:7]
	v_mfma_f32_16x16x32_bf16 v[0:3], v[108:111], v[96:99], v[0:3]
	v_mfma_f32_16x16x32_bf16 v[20:23], v[112:115], v[96:99], v[20:23]
	s_cbranch_scc0 .LBB0_3063
	s_waitcnt vmcnt(4)
	s_waitcnt lgkmcnt(0)
	s_barrier
	ds_read_b128 v[72:75], v80 offset:32768
	ds_read_b128 v[84:87], v80 offset:33792
	ds_read_b128 v[88:91], v80 offset:34816
	ds_read_b128 v[92:95], v80 offset:35840
	ds_read_b128 v[96:99], v81 offset:32768
	ds_read_b128 v[100:103], v81 offset:33792
	ds_read_b128 v[104:107], v81 offset:34816
	ds_read_b128 v[108:111], v81 offset:35840
	s_waitcnt lgkmcnt(0)
	s_waitcnt vmcnt(0)
	s_waitcnt lgkmcnt(0)
	s_barrier
	v_mfma_f32_16x16x32_bf16 v[112:115], v[96:99], v[72:75], v[60:63]
	v_readlane_b32 s40, v241, 1
	v_readlane_b32 s48, v241, 9
	v_mfma_f32_16x16x32_bf16 v[116:119], v[100:103], v[72:75], v[56:59]
	v_readlane_b32 s49, v241, 10
	s_add_i32 s2, s2, s3
	s_add_i32 s22, s22, s23
	v_mfma_f32_16x16x32_bf16 v[120:123], v[104:107], v[72:75], v[52:55]
	v_readlane_b32 s41, v241, 2
	v_readlane_b32 s42, v241, 3
	v_readlane_b32 s43, v241, 4
	v_mfma_f32_16x16x32_bf16 v[124:127], v[108:111], v[72:75], v[48:51]
	v_add_u32_e32 v74, s37, v78
	v_cmp_lt_i32_e32 vcc, s35, v74
	v_readlane_b32 s44, v241, 5
	v_mfma_f32_16x16x32_bf16 v[60:63], v[104:107], v[88:91], v[16:19]
	v_readlane_b32 s45, v241, 6
	v_readlane_b32 s46, v241, 7
	v_readlane_b32 s47, v241, 8
	v_add_u32_e32 v16, 0xfffff000, v74
	v_lshrrev_b32_e32 v16, 12, v16
	v_mfma_f32_16x16x32_bf16 v[152:155], v[100:103], v[88:91], v[24:27]
	v_add_u32_e32 v16, 6, v16
	v_readlane_b32 s50, v241, 11
	v_readlane_b32 s51, v241, 12
	v_or_b32_e32 v24, s38, v79
	v_mfma_f32_16x16x32_bf16 v[56:59], v[108:111], v[88:91], v[12:15]
	v_ashrrev_i32_e32 v25, 31, v24
	v_lshlrev_b64 v[72:73], 2, v[24:25]
	v_readlane_b32 s52, v241, 13
	v_cndmask_b32_e32 v12, 5, v16, vcc
	v_mad_u64_u32 v[12:13], s[18:19], v12, s30, v[70:71]
	v_mfma_f32_16x16x32_bf16 v[48:51], v[96:99], v[92:95], v[8:11]
	v_readlane_b32 s53, v241, 14
	v_readlane_b32 s54, v241, 15
	v_readlane_b32 s55, v241, 16
	v_lshl_add_u64 v[8:9], v[12:13], 0, v[72:73]
	v_lshl_add_u64 v[12:13], v[8:9], 0, v[64:65]
	v_mfma_f32_16x16x32_bf16 v[128:131], v[96:99], v[84:87], v[44:47]
	v_add_co_u32_e32 v18, vcc, s36, v12
	v_lshl_add_u64 v[16:17], v[12:13], 0, s[14:15]
	v_mfma_f32_16x16x32_bf16 v[132:135], v[100:103], v[84:87], v[40:43]
	v_addc_co_u32_e32 v19, vcc, 0, v13, vcc
	v_mfma_f32_16x16x32_bf16 v[136:139], v[104:107], v[84:87], v[36:39]
	v_mfma_f32_16x16x32_bf16 v[84:87], v[108:111], v[84:87], v[32:35]
	v_mfma_f32_16x16x32_bf16 v[140:143], v[96:99], v[88:91], v[28:31]
	ds_read_b128 v[144:147], v80 offset:49152
	ds_read_b128 v[148:151], v80 offset:50176
	ds_read_b128 v[52:55], v80 offset:51200
	ds_read_b128 v[28:31], v80 offset:52224
	ds_read_b128 v[44:47], v81 offset:49152
	ds_read_b128 v[40:43], v81 offset:50176
	ds_read_b128 v[36:39], v81 offset:51200
	ds_read_b128 v[32:35], v81 offset:52224
	s_waitcnt lgkmcnt(0)
	s_waitcnt lgkmcnt(0)
	s_barrier
	v_or_b32_e32 v96, v74, v76
	v_mfma_f32_16x16x32_bf16 v[24:27], v[100:103], v[92:95], v[4:7]
	v_or_b32_e32 v156, 16, v96
	v_or_b32_e32 v158, 32, v96
	v_or_b32_e32 v74, 48, v96
	v_mfma_f32_16x16x32_bf16 v[4:7], v[104:107], v[92:95], v[0:3]
	s_nop 2
	global_load_dwordx4 v[0:3], v[16:17], off offset:64
	global_load_dwordx4 v[12:15], v[16:17], off offset:128
	v_mfma_f32_16x16x32_bf16 v[8:11], v[108:111], v[92:95], v[20:23]
	s_nop 2
	global_load_dwordx4 v[20:23], v[18:19], off
	s_nop 0
	global_load_dwordx4 v[16:19], v[16:17], off offset:192
	s_nop 0
	v_mov_b32_e32 v236, v96
	v_ashrrev_i32_e32 v237, 31, v96
	v_lshlrev_b64 v[236:237], 12, v[236:237]
	v_lshl_add_u64 v[236:237], s[48:49], 0, v[236:237]
	v_lshl_add_u64 v[236:237], v[236:237], 0, v[72:73]
	v_lshl_add_u64 v[236:237], v[236:237], 0, v[64:65]
	v_mov_b32_e32 v238, v156
	v_ashrrev_i32_e32 v239, 31, v156
	v_lshlrev_b64 v[238:239], 12, v[238:239]
	v_lshl_add_u64 v[238:239], s[48:49], 0, v[238:239]
	v_lshl_add_u64 v[238:239], v[238:239], 0, v[72:73]
	v_lshl_add_u64 v[238:239], v[238:239], 0, v[64:65]
	v_mov_b32_e32 v242, v158
	v_ashrrev_i32_e32 v243, 31, v158
	v_lshlrev_b64 v[242:243], 12, v[242:243]
	v_lshl_add_u64 v[242:243], s[48:49], 0, v[242:243]
	v_lshl_add_u64 v[242:243], v[242:243], 0, v[72:73]
	v_lshl_add_u64 v[242:243], v[242:243], 0, v[64:65]
	v_mov_b32_e32 v244, v74
	v_ashrrev_i32_e32 v245, 31, v74
	v_lshlrev_b64 v[244:245], 12, v[244:245]
	v_lshl_add_u64 v[244:245], s[48:49], 0, v[244:245]
	v_lshl_add_u64 v[244:245], v[244:245], 0, v[72:73]
	v_lshl_add_u64 v[244:245], v[244:245], 0, v[64:65]
	global_load_dwordx4 v[170:173], v[236:237], off
	global_load_dwordx4 v[174:177], v[236:237], off offset:64
	global_load_dwordx4 v[178:181], v[236:237], off offset:128
	global_load_dwordx4 v[182:185], v[236:237], off offset:192
	global_load_dwordx4 v[186:189], v[238:239], off
	global_load_dwordx4 v[190:193], v[238:239], off offset:64
	global_load_dwordx4 v[194:197], v[238:239], off offset:128
	global_load_dwordx4 v[198:201], v[238:239], off offset:192
	global_load_dwordx4 v[202:205], v[242:243], off
	global_load_dwordx4 v[206:209], v[242:243], off offset:64
	global_load_dwordx4 v[210:213], v[242:243], off offset:128
	global_load_dwordx4 v[214:217], v[242:243], off offset:192
	global_load_dwordx4 v[218:221], v[244:245], off
	global_load_dwordx4 v[222:225], v[244:245], off offset:64
	global_load_dwordx4 v[228:231], v[244:245], off offset:128
	global_load_dwordx4 v[232:235], v[244:245], off offset:192
	v_mfma_f32_16x16x32_bf16 v[88:91], v[44:47], v[144:147], v[112:115]
	s_waitcnt vmcnt(15)
	v_pk_mul_f32 v[170:171], v[170:171], s[16:17] op_sel_hi:[1,0]
	v_mfma_f32_16x16x32_bf16 v[96:99], v[36:39], v[144:147], v[120:123]
	v_mul_f32_e64 v172, v172, s16
	v_mul_f32_e64 v173, v173, s16
	s_waitcnt vmcnt(14)
	v_pk_mul_f32 v[174:175], v[174:175], s[16:17] op_sel_hi:[1,0]
	v_pk_mul_f32 v[176:177], v[176:177], s[16:17] op_sel_hi:[1,0]
	v_mfma_f32_16x16x32_bf16 v[92:95], v[40:43], v[144:147], v[116:119]
	s_waitcnt vmcnt(13)
	v_mul_f32_e64 v178, v178, s16
	v_mul_f32_e64 v179, v179, s16
	v_pk_mul_f32 v[180:181], v[180:181], s[16:17] op_sel_hi:[1,0]
	v_pk_fma_f32 v[88:89], v[88:89], v[20:21], v[170:171]
	v_mfma_f32_16x16x32_bf16 v[104:107], v[32:35], v[144:147], v[124:127]
	v_fma_f32 v90, v90, v22, v172
	v_fma_f32 v91, v91, v23, v173
	v_pk_fma_f32 v[92:93], v[92:93], v[0:1], v[174:175]
	v_pk_fma_f32 v[94:95], v[94:95], v[2:3], v[176:177]
	v_pk_fma_f32 v[96:97], v[96:97], v[12:13], v[178:179]
	v_pk_fma_f32 v[98:99], v[98:99], v[14:15], v[180:181]
	v_mfma_f32_16x16x32_bf16 v[116:119], v[44:47], v[148:151], v[128:131]
	s_waitcnt vmcnt(12)
	v_pk_mul_f32 v[182:183], v[182:183], s[16:17] op_sel_hi:[1,0]
	v_pk_mul_f32 v[184:185], v[184:185], s[16:17] op_sel_hi:[1,0]
	v_pk_fma_f32 v[170:171], v[104:105], v[16:17], v[182:183]
	v_pk_fma_f32 v[172:173], v[106:107], v[18:19], v[184:185]
	global_store_dwordx4 v[236:237], v[88:91], off sc0 sc1
	global_store_dwordx4 v[236:237], v[92:95], off offset:64 sc0 sc1
	global_store_dwordx4 v[236:237], v[96:99], off offset:128 sc0 sc1
	global_store_dwordx4 v[236:237], v[170:173], off offset:192 sc0 sc1
	v_mfma_f32_16x16x32_bf16 v[124:127], v[40:43], v[148:151], v[132:135]
	v_mfma_f32_16x16x32_bf16 v[92:95], v[36:39], v[148:151], v[136:139]
	s_waitcnt vmcnt(15)
	v_pk_mul_f32 v[186:187], v[186:187], s[16:17] op_sel_hi:[1,0]
	v_mfma_f32_16x16x32_bf16 v[84:87], v[32:35], v[148:151], v[84:87]
	v_mul_f32_e64 v188, v188, s16
	v_mul_f32_e64 v189, v189, s16
	s_waitcnt vmcnt(14)
	v_pk_mul_f32 v[190:191], v[190:191], s[16:17] op_sel_hi:[1,0]
	v_pk_mul_f32 v[192:193], v[192:193], s[16:17] op_sel_hi:[1,0]
	s_waitcnt vmcnt(13)
	v_pk_mul_f32 v[194:195], v[194:195], s[16:17] op_sel_hi:[1,0]
	v_pk_mul_f32 v[196:197], v[196:197], s[16:17] op_sel_hi:[1,0]
	s_waitcnt vmcnt(12)
	v_pk_mul_f32 v[198:199], v[198:199], s[16:17] op_sel_hi:[1,0]
	v_pk_mul_f32 v[200:201], v[200:201], s[16:17] op_sel_hi:[1,0]
	v_pk_fma_f32 v[186:187], v[116:117], v[20:21], v[186:187]
	v_pk_fma_f32 v[188:189], v[118:119], v[22:23], v[188:189]
	v_pk_fma_f32 v[190:191], v[124:125], v[0:1], v[190:191]
	v_pk_fma_f32 v[192:193], v[126:127], v[2:3], v[192:193]
	v_pk_fma_f32 v[92:93], v[92:93], v[12:13], v[194:195]
	v_pk_fma_f32 v[94:95], v[94:95], v[14:15], v[196:197]
	v_pk_fma_f32 v[84:85], v[84:85], v[16:17], v[198:199]
	v_pk_fma_f32 v[86:87], v[86:87], v[18:19], v[200:201]
	global_store_dwordx4 v[238:239], v[186:189], off sc0 sc1
	global_store_dwordx4 v[238:239], v[190:193], off offset:64 sc0 sc1
	global_store_dwordx4 v[238:239], v[92:95], off offset:128 sc0 sc1
	global_store_dwordx4 v[238:239], v[84:87], off offset:192 sc0 sc1
	v_mfma_f32_16x16x32_bf16 v[174:177], v[44:47], v[52:55], v[140:143]
	v_mfma_f32_16x16x32_bf16 v[186:189], v[40:43], v[52:55], v[152:155]
	v_mfma_f32_16x16x32_bf16 v[60:63], v[36:39], v[52:55], v[60:63]
	v_mfma_f32_16x16x32_bf16 v[52:55], v[32:35], v[52:55], v[56:59]
	v_mfma_f32_16x16x32_bf16 v[44:47], v[44:47], v[28:31], v[48:51]
	s_waitcnt vmcnt(15)
	v_pk_mul_f32 v[56:57], v[202:203], s[16:17] op_sel_hi:[1,0]
	v_pk_mul_f32 v[58:59], v[204:205], s[16:17] op_sel_hi:[1,0]
	s_waitcnt vmcnt(14)
	v_pk_mul_f32 v[202:203], v[206:207], s[16:17] op_sel_hi:[1,0]
	v_pk_mul_f32 v[204:205], v[208:209], s[16:17] op_sel_hi:[1,0]
	s_waitcnt vmcnt(13)
	v_pk_mul_f32 v[206:207], v[210:211], s[16:17] op_sel_hi:[1,0]
	v_pk_mul_f32 v[208:209], v[212:213], s[16:17] op_sel_hi:[1,0]
	s_waitcnt vmcnt(12)
	v_pk_mul_f32 v[210:211], v[214:215], s[16:17] op_sel_hi:[1,0]
	v_pk_mul_f32 v[212:213], v[216:217], s[16:17] op_sel_hi:[1,0]
	v_pk_fma_f32 v[56:57], v[174:175], v[20:21], v[56:57]
	v_pk_fma_f32 v[58:59], v[176:177], v[22:23], v[58:59]
	v_pk_fma_f32 v[202:203], v[186:187], v[0:1], v[202:203]
	v_pk_fma_f32 v[204:205], v[188:189], v[2:3], v[204:205]
	v_pk_fma_f32 v[60:61], v[60:61], v[12:13], v[206:207]
	v_pk_fma_f32 v[62:63], v[62:63], v[14:15], v[208:209]
	v_pk_fma_f32 v[52:53], v[52:53], v[16:17], v[210:211]
	v_pk_fma_f32 v[54:55], v[54:55], v[18:19], v[212:213]
	global_store_dwordx4 v[242:243], v[56:59], off sc0 sc1
	global_store_dwordx4 v[242:243], v[202:205], off offset:64 sc0 sc1
	global_store_dwordx4 v[242:243], v[60:63], off offset:128 sc0 sc1
	global_store_dwordx4 v[242:243], v[52:55], off offset:192 sc0 sc1
	v_mfma_f32_16x16x32_bf16 v[24:27], v[40:43], v[28:31], v[24:27]
	v_mfma_f32_16x16x32_bf16 v[4:7], v[36:39], v[28:31], v[4:7]
	s_add_i32 s17, s17, s34
	s_cmpk_gt_i32 s2, 0x9f
	s_waitcnt vmcnt(13)
	v_pk_mul_f32 v[36:37], v[228:229], s[16:17] op_sel_hi:[1,0]
	v_mfma_f32_16x16x32_bf16 v[8:11], v[32:35], v[28:31], v[8:11]
	v_mul_f32_e64 v28, v218, s16
	v_mul_f32_e64 v29, v219, s16
	v_pk_mul_f32 v[30:31], v[220:221], s[16:17] op_sel_hi:[1,0]
	v_pk_mul_f32 v[32:33], v[222:223], s[16:17] op_sel_hi:[1,0]
	v_pk_mul_f32 v[34:35], v[224:225], s[16:17] op_sel_hi:[1,0]
	v_pk_mul_f32 v[38:39], v[230:231], s[16:17] op_sel_hi:[1,0]
	s_waitcnt vmcnt(12)
	v_pk_mul_f32 v[232:233], v[232:233], s[16:17] op_sel_hi:[1,0]
	v_pk_mul_f32 v[234:235], v[234:235], s[16:17] op_sel_hi:[1,0]
	v_pk_fma_f32 v[20:21], v[44:45], v[20:21], v[28:29]
	v_pk_fma_f32 v[22:23], v[46:47], v[22:23], v[30:31]
	v_pk_fma_f32 v[0:1], v[24:25], v[0:1], v[32:33]
	v_pk_fma_f32 v[2:3], v[26:27], v[2:3], v[34:35]
	v_pk_fma_f32 v[4:5], v[4:5], v[12:13], v[36:37]
	v_pk_fma_f32 v[6:7], v[6:7], v[14:15], v[38:39]
	v_pk_fma_f32 v[8:9], v[8:9], v[16:17], v[232:233]
	v_pk_fma_f32 v[10:11], v[10:11], v[18:19], v[234:235]
	global_store_dwordx4 v[244:245], v[20:23], off sc0 sc1
	global_store_dwordx4 v[244:245], v[0:3], off offset:64 sc0 sc1
	global_store_dwordx4 v[244:245], v[4:7], off offset:128 sc0 sc1
	global_store_dwordx4 v[244:245], v[8:11], off offset:192 sc0 sc1
	s_cbranch_scc0 .LBB0_3062
